# GEMM hand-off trim: setprio moved outside the barrier-to-MFMA path, redundant lgkmcnt(0) after the barrier removed
# baseline (speedup 1.0000x reference)
; #define PG8_STAGE(bufoff, gbase, voff) do { _Pragma("unroll") for (int _i = 0; _i < 2; ++_i) \
;         __builtin_amdgcn_global_load_lds((const unsigned*)((const char*)(gbase) + (voff)[_i]), (PG8_LAS unsigned*)(lds + (bufoff) + ldsw + _i * 8192), 16, 0, 0); } while (0)
; #define PG8_LDA(dst, b, h) do { _Pragma("unroll") for (int m = 0; m < 4; ++m) _Pragma("unroll") for (int k = 0; k < 2; ++k) dst[m][k] = *(const PG8_LAS bf16x8*)(lds + PG8_SA(b, h) + aoff + m * 2048 + k * 1024); } while (0)
; #define PG8_LDB(dst, b, h) do { _Pragma("unroll") for (int n = 0; n < 2; ++n) _Pragma("unroll") for (int k = 0; k < 2; ++k) dst[n][k] = *(const PG8_LAS bf16x8*)(lds + PG8_SB(b, h) + boff + n * 2048 + k * 1024); } while (0)
; template <class Epi, class Sched, bool ALIGN_EPI = false, bool SP2 = false>
; __device__ __forceinline__ void gemm_phase(PG8_LAS unsigned char* lds, const Gemm g, const Sched& S, const Epi& E) {
;     ...
;             const bool last = (t == nt - 2);
;             const char* a1 = cA + (size_t)(t + 1) * kstep;
;             const char* a2 = last ? nA : cA + (size_t)(t + 2) * kstep; const char* b2 = last ? nB : cB + (size_t)(t + 2) * kstep;
;             const char* a3 = a2 + kstep; const char* b3 = b2 + kstep;
;             if (last && has_next) S.a_ready(nxt);
;             if (last) E.pre(cur, wid, lane);
;             if constexpr (SP2) {
;             PG8_LDB(B0, 0, 0); PG8_LDB(B1, 0, 1); PG8_SCHED; PG8_LDA(At, 0, 0); PG8_STAGE(PG8_SA(1, 1), a1 + hstep, voffA);
;             PG8_WAIT_V(8); PG8_WAIT_L(0); PG8_BAR; PG8_MMA(0, 0, At, B0); PG8_MMA(0, 1, At, B1); PG8_BAR; PG8_SCHED;
;             PG8_LDA(At, 0, 1); PG8_STAGE(PG8_SB(0, 0), b2, voffB); PG8_STAGE(PG8_SB(0, 1), b2 + hstep, voffB); PG8_STAGE(PG8_SA(0, 0), a2, voffA);
;             PG8_WAIT_V(8); PG8_WAIT_L(0); PG8_BAR; PG8_MMA(1, 0, At, B0); PG8_MMA(1, 1, At, B1); PG8_BAR; PG8_SCHED;
;             PG8_LDB(B0, 1, 0); PG8_LDB(B1, 1, 1); PG8_SCHED; PG8_LDA(At, 1, 0); PG8_STAGE(PG8_SA(0, 1), a2 + hstep, voffA);
;             PG8_WAIT_V(8); PG8_WAIT_L(0); PG8_BAR; PG8_MMA(0, 0, At, B0); PG8_MMA(0, 1, At, B1); PG8_BAR; PG8_SCHED;
;             PG8_LDA(At, 1, 1); PG8_STAGE(PG8_SB(1, 0), b3, voffB); PG8_STAGE(PG8_SB(1, 1), b3 + hstep, voffB); PG8_STAGE(PG8_SA(1, 0), a3, voffA);
;             PG8_WAIT_V(8); PG8_WAIT_L(0); PG8_BAR; PG8_MMA(1, 0, At, B0); PG8_MMA(1, 1, At, B1); PG8_BAR; PG8_SCHED;
.LBB0_244:
	s_add_u32 s6, s4, 0xfffc0080
	s_addc_u32 s7, s5, -1
	s_and_b64 s[0:1], s[0:1], exec
	s_cselect_b32 s7, s38, s7
	s_cselect_b32 s6, s39, s6
	s_cselect_b32 s1, s49, s57
	s_cselect_b32 s0, s55, s56
	s_add_i32 s59, 0, 0x10000
	v_add_u32_e32 v144, s59, v197
	s_add_i32 s62, 0, 0x14000
	ds_read_b128 v[132:135], v144
	ds_read_b128 v[136:139], v144 offset:1024
	ds_read_b128 v[140:143], v144 offset:2048
	ds_read_b128 v[202:205], v144 offset:3072
	v_add_u32_e32 v144, s62, v197
	ds_read_b128 v[206:209], v144
	ds_read_b128 v[210:213], v144 offset:1024
	ds_read_b128 v[214:217], v144 offset:2048
	ds_read_b128 v[218:221], v144 offset:3072
	v_lshl_add_u64 v[172:173], s[4:5], 0, v[166:167]
	s_add_i32 m0, s25, 0xc000
	ds_read_b128 v[222:225], v199
	ds_read_b128 v[226:229], v199 offset:1024
	ds_read_b128 v[230:233], v199 offset:2048
	ds_read_b128 v[234:237], v199 offset:3072
	ds_read_b128 v[238:241], v199 offset:4096
	ds_read_b128 v[242:245], v199 offset:5120
	ds_read_b128 v[246:249], v199 offset:6144
	ds_read_b128 v[180:183], v199 offset:7168
	global_load_lds_dwordx4 v[172:173], off
	v_lshl_add_u64 v[172:173], s[4:5], 0, v[168:169]
	s_add_i32 m0, s25, 0xe000
	s_nop 0
	global_load_lds_dwordx4 v[172:173], off
	s_waitcnt vmcnt(8)
	s_waitcnt lgkmcnt(0)
	s_setprio 1
	s_barrier
	v_mfma_f32_16x16x32_bf16 v[124:127], v[132:135], v[222:225], v[124:127]
	v_mfma_f32_16x16x32_bf16 v[120:123], v[140:143], v[222:225], v[120:123]
	v_mfma_f32_16x16x32_bf16 v[108:111], v[132:135], v[230:233], v[108:111]
	v_mfma_f32_16x16x32_bf16 v[104:107], v[140:143], v[230:233], v[104:107]
	v_mfma_f32_16x16x32_bf16 v[92:95], v[132:135], v[238:241], v[92:95]
	v_mfma_f32_16x16x32_bf16 v[88:91], v[140:143], v[238:241], v[88:91]
	v_mfma_f32_16x16x32_bf16 v[76:79], v[132:135], v[246:249], v[76:79]
	v_mfma_f32_16x16x32_bf16 v[72:75], v[140:143], v[246:249], v[72:75]
	v_mfma_f32_16x16x32_bf16 v[124:127], v[136:139], v[226:229], v[124:127]
	v_mfma_f32_16x16x32_bf16 v[120:123], v[202:205], v[226:229], v[120:123]
	v_mfma_f32_16x16x32_bf16 v[108:111], v[136:139], v[234:237], v[108:111]
	v_mfma_f32_16x16x32_bf16 v[104:107], v[202:205], v[234:237], v[104:107]
	v_mfma_f32_16x16x32_bf16 v[92:95], v[136:139], v[242:245], v[92:95]
	v_mfma_f32_16x16x32_bf16 v[88:91], v[202:205], v[242:245], v[88:91]
	v_mfma_f32_16x16x32_bf16 v[76:79], v[136:139], v[180:183], v[76:79]
	v_mfma_f32_16x16x32_bf16 v[72:75], v[202:205], v[180:183], v[72:75]
	s_setprio 0
	s_setprio 1
	v_mfma_f32_16x16x32_bf16 v[116:119], v[206:209], v[222:225], v[116:119]
	v_mfma_f32_16x16x32_bf16 v[112:115], v[214:217], v[222:225], v[112:115]
	v_mfma_f32_16x16x32_bf16 v[100:103], v[206:209], v[230:233], v[100:103]
	v_mfma_f32_16x16x32_bf16 v[96:99], v[214:217], v[230:233], v[96:99]
	v_mfma_f32_16x16x32_bf16 v[84:87], v[206:209], v[238:241], v[84:87]
	v_mfma_f32_16x16x32_bf16 v[80:83], v[214:217], v[238:241], v[80:83]
	v_mfma_f32_16x16x32_bf16 v[68:71], v[206:209], v[246:249], v[68:71]
	v_mfma_f32_16x16x32_bf16 v[64:67], v[214:217], v[246:249], v[64:67]
	v_mfma_f32_16x16x32_bf16 v[116:119], v[210:213], v[226:229], v[116:119]
	v_mfma_f32_16x16x32_bf16 v[112:115], v[218:221], v[226:229], v[112:115]
	v_mfma_f32_16x16x32_bf16 v[100:103], v[210:213], v[234:237], v[100:103]
	v_mfma_f32_16x16x32_bf16 v[96:99], v[218:221], v[234:237], v[96:99]
	v_mfma_f32_16x16x32_bf16 v[84:87], v[210:213], v[242:245], v[84:87]
	v_mfma_f32_16x16x32_bf16 v[80:83], v[218:221], v[242:245], v[80:83]
	v_mfma_f32_16x16x32_bf16 v[68:71], v[210:213], v[180:183], v[68:71]
	v_mfma_f32_16x16x32_bf16 v[64:67], v[218:221], v[180:183], v[64:67]
	s_barrier
	s_setprio 0
	s_add_i32 s59, s59, s24
	v_lshl_add_u64 v[172:173], s[0:1], 0, v[154:155]
	s_mov_b32 m0, s59
	ds_read_b128 v[180:183], v199 offset:16384
	ds_read_b128 v[222:225], v199 offset:17408
	ds_read_b128 v[226:229], v199 offset:18432
	ds_read_b128 v[230:233], v199 offset:19456
	ds_read_b128 v[234:237], v199 offset:20480
	ds_read_b128 v[238:241], v199 offset:21504
	ds_read_b128 v[242:245], v199 offset:22528
	ds_read_b128 v[246:249], v199 offset:23552
	global_load_lds_dwordx4 v[172:173], off
	s_add_i32 m0, s59, 0x2000
	s_add_u32 s60, s0, 0x40000
	v_lshl_add_u64 v[184:185], s[0:1], 0, v[150:151]
	s_addc_u32 s61, s1, 0
	s_add_i32 s59, s62, s24
	global_load_lds_dwordx4 v[184:185], off
	v_lshl_add_u64 v[186:187], s[60:61], 0, v[154:155]
	s_mov_b32 m0, s59
	v_lshl_add_u64 v[188:189], s[6:7], 0, v[152:153]
	global_load_lds_dwordx4 v[186:187], off
	v_lshl_add_u64 v[186:187], s[60:61], 0, v[150:151]
	s_add_i32 m0, s59, 0x2000
	s_nop 0
	global_load_lds_dwordx4 v[186:187], off
	v_lshl_add_u64 v[186:187], s[6:7], 0, v[156:157]
	s_mov_b32 m0, s25
	s_nop 0
	global_load_lds_dwordx4 v[186:187], off
	s_mov_b32 m0, s26
	s_nop 0
	global_load_lds_dwordx4 v[188:189], off
	s_waitcnt vmcnt(8)
	s_waitcnt lgkmcnt(0)
	s_setprio 1
	s_barrier
; #define PG8_STAGE(bufoff, gbase, voff) do { _Pragma("unroll") for (int _i = 0; _i < 2; ++_i) \
;         __builtin_amdgcn_global_load_lds((const unsigned*)((const char*)(gbase) + (voff)[_i]), (PG8_LAS unsigned*)(lds + (bufoff) + ldsw + _i * 8192), 16, 0, 0); } while (0)
; #define PG8_LDA(dst, b, h) do { _Pragma("unroll") for (int m = 0; m < 4; ++m) _Pragma("unroll") for (int k = 0; k < 2; ++k) dst[m][k] = *(const PG8_LAS bf16x8*)(lds + PG8_SA(b, h) + aoff + m * 2048 + k * 1024); } while (0)
; #define PG8_LDB(dst, b, h) do { _Pragma("unroll") for (int n = 0; n < 2; ++n) _Pragma("unroll") for (int k = 0; k < 2; ++k) dst[n][k] = *(const PG8_LAS bf16x8*)(lds + PG8_SB(b, h) + boff + n * 2048 + k * 1024); } while (0)
; #define PG8_MMA(ai, bj, At, Bt) do { __builtin_amdgcn_s_setprio(1); _Pragma("unroll") for (int m = 0; m < 4; ++m) _Pragma("unroll") for (int n = 0; n < 2; ++n) _Pragma("unroll") for (int k = 0; k < 2; ++k) \
;         acc[ai][bj][m][n] = __builtin_amdgcn_mfma_f32_16x16x32_bf16(Bt[n][k], At[m][k], acc[ai][bj][m][n], 0, 0, 0); __builtin_amdgcn_s_setprio(0); } while (0)
; #define PG8_WAIT_V(n) asm volatile("s_waitcnt vmcnt(" #n ")" ::: "memory")
; #define PG8_WAIT_L(n) asm volatile("s_waitcnt lgkmcnt(" #n ")" ::: "memory")
; #define PG8_BAR __builtin_amdgcn_s_barrier()
; #define PG8_SCHED __builtin_amdgcn_sched_barrier(0)
; template <class Epi, class Sched, bool ALIGN_EPI = false, bool SP2 = false>
; __device__ __forceinline__ void gemm_phase(PG8_LAS unsigned char* lds, const Gemm g, const Sched& S, const Epi& E) {
;     ...
;             PG8_WAIT_V(8); PG8_WAIT_L(0); PG8_BAR; PG8_MMA(1, 0, At, B0); PG8_MMA(1, 1, At, B1); PG8_BAR; PG8_SCHED;
;             PG8_LDB(B0, 1, 0); PG8_LDB(B1, 1, 1); PG8_SCHED; PG8_LDA(At, 1, 0); PG8_STAGE(PG8_SA(0, 1), a2 + hstep, voffA);
;             PG8_WAIT_V(8); PG8_WAIT_L(0); PG8_BAR; PG8_MMA(0, 0, At, B0); PG8_MMA(0, 1, At, B1); PG8_BAR; PG8_SCHED;
	v_mfma_f32_16x16x32_bf16 v[60:63], v[132:135], v[180:183], v[60:63]
	v_mfma_f32_16x16x32_bf16 v[56:59], v[140:143], v[180:183], v[56:59]
	v_mfma_f32_16x16x32_bf16 v[44:47], v[132:135], v[226:229], v[44:47]
	v_mfma_f32_16x16x32_bf16 v[40:43], v[140:143], v[226:229], v[40:43]
	v_mfma_f32_16x16x32_bf16 v[28:31], v[132:135], v[234:237], v[28:31]
	v_mfma_f32_16x16x32_bf16 v[24:27], v[140:143], v[234:237], v[24:27]
	v_mfma_f32_16x16x32_bf16 v[12:15], v[132:135], v[242:245], v[12:15]
	v_mfma_f32_16x16x32_bf16 v[8:11], v[140:143], v[242:245], v[8:11]
	v_mfma_f32_16x16x32_bf16 v[60:63], v[136:139], v[222:225], v[60:63]
	v_mfma_f32_16x16x32_bf16 v[56:59], v[202:205], v[222:225], v[56:59]
	v_mfma_f32_16x16x32_bf16 v[44:47], v[136:139], v[230:233], v[44:47]
	v_mfma_f32_16x16x32_bf16 v[40:43], v[202:205], v[230:233], v[40:43]
	v_mfma_f32_16x16x32_bf16 v[28:31], v[136:139], v[238:241], v[28:31]
	v_mfma_f32_16x16x32_bf16 v[24:27], v[202:205], v[238:241], v[24:27]
	v_mfma_f32_16x16x32_bf16 v[12:15], v[136:139], v[246:249], v[12:15]
	v_mfma_f32_16x16x32_bf16 v[8:11], v[202:205], v[246:249], v[8:11]
	s_setprio 0
	s_setprio 1
	v_mfma_f32_16x16x32_bf16 v[52:55], v[206:209], v[180:183], v[52:55]
	v_mfma_f32_16x16x32_bf16 v[48:51], v[214:217], v[180:183], v[48:51]
	v_mfma_f32_16x16x32_bf16 v[36:39], v[206:209], v[226:229], v[36:39]
	v_mfma_f32_16x16x32_bf16 v[32:35], v[214:217], v[226:229], v[32:35]
	v_mfma_f32_16x16x32_bf16 v[20:23], v[206:209], v[234:237], v[20:23]
	v_mfma_f32_16x16x32_bf16 v[16:19], v[214:217], v[234:237], v[16:19]
	v_mfma_f32_16x16x32_bf16 v[4:7], v[206:209], v[242:245], v[4:7]
	v_mfma_f32_16x16x32_bf16 v[0:3], v[214:217], v[242:245], v[0:3]
	v_mfma_f32_16x16x32_bf16 v[52:55], v[210:213], v[222:225], v[52:55]
	v_mfma_f32_16x16x32_bf16 v[48:51], v[218:221], v[222:225], v[48:51]
	v_mfma_f32_16x16x32_bf16 v[36:39], v[210:213], v[230:233], v[36:39]
	v_mfma_f32_16x16x32_bf16 v[32:35], v[218:221], v[230:233], v[32:35]
	v_mfma_f32_16x16x32_bf16 v[20:23], v[210:213], v[238:241], v[20:23]
	v_mfma_f32_16x16x32_bf16 v[16:19], v[218:221], v[238:241], v[16:19]
	v_mfma_f32_16x16x32_bf16 v[4:7], v[210:213], v[246:249], v[4:7]
	v_mfma_f32_16x16x32_bf16 v[0:3], v[218:221], v[246:249], v[0:3]
	s_barrier
	s_setprio 0
	s_add_i32 s59, 0, 0x18000
	v_add_u32_e32 v144, s59, v197
	s_add_i32 s60, 0, 0x1c000
	ds_read_b128 v[132:135], v144
	ds_read_b128 v[136:139], v144 offset:1024
	ds_read_b128 v[140:143], v144 offset:2048
	ds_read_b128 v[180:183], v144 offset:3072
	v_add_u32_e32 v144, s60, v197
	ds_read_b128 v[202:205], v144
	ds_read_b128 v[206:209], v144 offset:1024
	ds_read_b128 v[210:213], v144 offset:2048
	ds_read_b128 v[214:217], v144 offset:3072
	s_add_u32 s6, s6, 0x40000
	s_addc_u32 s7, s7, 0
	s_mov_b32 m0, s27
	v_lshl_add_u64 v[190:191], s[6:7], 0, v[156:157]
	ds_read_b128 v[218:221], v199 offset:32768
	ds_read_b128 v[222:225], v199 offset:33792
	ds_read_b128 v[226:229], v199 offset:34816
	ds_read_b128 v[230:233], v199 offset:35840
	ds_read_b128 v[234:237], v199 offset:36864
	ds_read_b128 v[238:241], v199 offset:37888
	ds_read_b128 v[242:245], v199 offset:38912
	ds_read_b128 v[246:249], v199 offset:39936
	global_load_lds_dwordx4 v[190:191], off
	v_lshl_add_u64 v[190:191], s[6:7], 0, v[152:153]
	s_mov_b32 m0, s28
	s_nop 0
	global_load_lds_dwordx4 v[190:191], off
	s_waitcnt vmcnt(8)
	s_waitcnt lgkmcnt(0)
	s_setprio 1
	s_barrier
	v_mfma_f32_16x16x32_bf16 v[124:127], v[132:135], v[218:221], v[124:127]
	v_mfma_f32_16x16x32_bf16 v[120:123], v[140:143], v[218:221], v[120:123]
	v_mfma_f32_16x16x32_bf16 v[108:111], v[132:135], v[226:229], v[108:111]
	v_mfma_f32_16x16x32_bf16 v[104:107], v[140:143], v[226:229], v[104:107]
	v_mfma_f32_16x16x32_bf16 v[92:95], v[132:135], v[234:237], v[92:95]
	v_mfma_f32_16x16x32_bf16 v[88:91], v[140:143], v[234:237], v[88:91]
	v_mfma_f32_16x16x32_bf16 v[76:79], v[132:135], v[242:245], v[76:79]
	v_mfma_f32_16x16x32_bf16 v[72:75], v[140:143], v[242:245], v[72:75]
	v_mfma_f32_16x16x32_bf16 v[124:127], v[136:139], v[222:225], v[124:127]
	v_mfma_f32_16x16x32_bf16 v[120:123], v[180:183], v[222:225], v[120:123]
	v_mfma_f32_16x16x32_bf16 v[108:111], v[136:139], v[230:233], v[108:111]
	v_mfma_f32_16x16x32_bf16 v[104:107], v[180:183], v[230:233], v[104:107]
	v_mfma_f32_16x16x32_bf16 v[92:95], v[136:139], v[238:241], v[92:95]
	v_mfma_f32_16x16x32_bf16 v[88:91], v[180:183], v[238:241], v[88:91]
	v_mfma_f32_16x16x32_bf16 v[76:79], v[136:139], v[246:249], v[76:79]
	v_mfma_f32_16x16x32_bf16 v[72:75], v[180:183], v[246:249], v[72:75]
	s_setprio 0
	s_setprio 1
	v_mfma_f32_16x16x32_bf16 v[116:119], v[202:205], v[218:221], v[116:119]
	v_mfma_f32_16x16x32_bf16 v[112:115], v[210:213], v[218:221], v[112:115]
	v_mfma_f32_16x16x32_bf16 v[100:103], v[202:205], v[226:229], v[100:103]
	v_mfma_f32_16x16x32_bf16 v[96:99], v[210:213], v[226:229], v[96:99]
	v_mfma_f32_16x16x32_bf16 v[84:87], v[202:205], v[234:237], v[84:87]
	v_mfma_f32_16x16x32_bf16 v[80:83], v[210:213], v[234:237], v[80:83]
	v_mfma_f32_16x16x32_bf16 v[68:71], v[202:205], v[242:245], v[68:71]
	v_mfma_f32_16x16x32_bf16 v[64:67], v[210:213], v[242:245], v[64:67]
	v_mfma_f32_16x16x32_bf16 v[116:119], v[206:209], v[222:225], v[116:119]
	v_mfma_f32_16x16x32_bf16 v[112:115], v[214:217], v[222:225], v[112:115]
	v_mfma_f32_16x16x32_bf16 v[100:103], v[206:209], v[230:233], v[100:103]
	v_mfma_f32_16x16x32_bf16 v[96:99], v[214:217], v[230:233], v[96:99]
	v_mfma_f32_16x16x32_bf16 v[84:87], v[206:209], v[238:241], v[84:87]
	v_mfma_f32_16x16x32_bf16 v[80:83], v[214:217], v[238:241], v[80:83]
	v_mfma_f32_16x16x32_bf16 v[68:71], v[206:209], v[246:249], v[68:71]
	v_mfma_f32_16x16x32_bf16 v[64:67], v[214:217], v[246:249], v[64:67]
	s_barrier
; #define PG8_STAGE(bufoff, gbase, voff) do { _Pragma("unroll") for (int _i = 0; _i < 2; ++_i) \
;         __builtin_amdgcn_global_load_lds((const unsigned*)((const char*)(gbase) + (voff)[_i]), (PG8_LAS unsigned*)(lds + (bufoff) + ldsw + _i * 8192), 16, 0, 0); } while (0)
; #define PG8_LDA(dst, b, h) do { _Pragma("unroll") for (int m = 0; m < 4; ++m) _Pragma("unroll") for (int k = 0; k < 2; ++k) dst[m][k] = *(const PG8_LAS bf16x8*)(lds + PG8_SA(b, h) + aoff + m * 2048 + k * 1024); } while (0)
; #define PG8_WAIT_V(n) asm volatile("s_waitcnt vmcnt(" #n ")" ::: "memory")
; #define PG8_WAIT_L(n) asm volatile("s_waitcnt lgkmcnt(" #n ")" ::: "memory")
; template <class Epi, class Sched, bool ALIGN_EPI = false, bool SP2 = false>
; __device__ __forceinline__ void gemm_phase(PG8_LAS unsigned char* lds, const Gemm g, const Sched& S, const Epi& E) {
;     ...
;         for (int t = 0; t < nt; t += 2) {
;             const bool last = (t == nt - 2);
;             const char* a1 = cA + (size_t)(t + 1) * kstep;
;             const char* a2 = last ? nA : cA + (size_t)(t + 2) * kstep; const char* b2 = last ? nB : cB + (size_t)(t + 2) * kstep;
;             const char* a3 = a2 + kstep; const char* b3 = b2 + kstep;
;             if (last && has_next) S.a_ready(nxt);
;             if (last) E.pre(cur, wid, lane);
;             if constexpr (SP2) {
;             PG8_LDB(B0, 0, 0); PG8_LDB(B1, 0, 1); PG8_SCHED; PG8_LDA(At, 0, 0); PG8_STAGE(PG8_SA(1, 1), a1 + hstep, voffA);
;             PG8_WAIT_V(8); PG8_WAIT_L(0); PG8_BAR; PG8_MMA(0, 0, At, B0); PG8_MMA(0, 1, At, B1); PG8_BAR; PG8_SCHED;
;             PG8_LDA(At, 0, 1); PG8_STAGE(PG8_SB(0, 0), b2, voffB); PG8_STAGE(PG8_SB(0, 1), b2 + hstep, voffB); PG8_STAGE(PG8_SA(0, 0), a2, voffA);
;             PG8_WAIT_V(8); PG8_WAIT_L(0); PG8_BAR; PG8_MMA(1, 0, At, B0); PG8_MMA(1, 1, At, B1); PG8_BAR; PG8_SCHED;
;             PG8_LDB(B0, 1, 0); PG8_LDB(B1, 1, 1); PG8_SCHED; PG8_LDA(At, 1, 0); PG8_STAGE(PG8_SA(0, 1), a2 + hstep, voffA);
;             PG8_WAIT_V(8); PG8_WAIT_L(0); PG8_BAR; PG8_MMA(0, 0, At, B0); PG8_MMA(0, 1, At, B1); PG8_BAR; PG8_SCHED;
;             PG8_LDA(At, 1, 1); PG8_STAGE(PG8_SB(1, 0), b3, voffB); PG8_STAGE(PG8_SB(1, 1), b3 + hstep, voffB); PG8_STAGE(PG8_SA(1, 0), a3, voffA);
;             PG8_WAIT_V(8); PG8_WAIT_L(0); PG8_BAR; PG8_MMA(1, 0, At, B0); PG8_MMA(1, 1, At, B1); PG8_BAR; PG8_SCHED;
	s_setprio 0
	s_add_i32 s6, s59, s24
	v_lshl_add_u64 v[172:173], v[172:173], 0, s[94:95]
	s_mov_b32 m0, s6
	ds_read_b128 v[218:221], v199 offset:49152
	ds_read_b128 v[222:225], v199 offset:50176
	ds_read_b128 v[226:229], v199 offset:51200
	ds_read_b128 v[230:233], v199 offset:52224
	ds_read_b128 v[234:237], v199 offset:53248
	ds_read_b128 v[238:241], v199 offset:54272
	ds_read_b128 v[242:245], v199 offset:55296
	ds_read_b128 v[246:249], v199 offset:56320
	global_load_lds_dwordx4 v[172:173], off
	s_add_i32 m0, s6, 0x2000
	s_add_u32 s0, s0, 0x40080
	v_lshl_add_u64 v[172:173], v[184:185], 0, s[94:95]
	s_addc_u32 s1, s1, 0
	s_add_i32 s6, s60, s24
	global_load_lds_dwordx4 v[172:173], off
	v_lshl_add_u64 v[172:173], s[0:1], 0, v[154:155]
	s_mov_b32 m0, s6
	s_nop 0
	global_load_lds_dwordx4 v[172:173], off
	v_lshl_add_u64 v[172:173], s[0:1], 0, v[150:151]
	s_add_i32 m0, s6, 0x2000
	s_nop 0
	global_load_lds_dwordx4 v[172:173], off
	v_lshl_add_u64 v[172:173], v[186:187], 0, s[94:95]
	s_mov_b32 m0, s29
	s_nop 0
	global_load_lds_dwordx4 v[172:173], off
	v_lshl_add_u64 v[172:173], v[188:189], 0, s[94:95]
	s_mov_b32 m0, s30
	s_nop 0
	global_load_lds_dwordx4 v[172:173], off
	s_waitcnt vmcnt(8)
	s_waitcnt lgkmcnt(0)
	s_setprio 1
	s_barrier
	v_mfma_f32_16x16x32_bf16 v[60:63], v[132:135], v[218:221], v[60:63]
	v_mfma_f32_16x16x32_bf16 v[56:59], v[140:143], v[218:221], v[56:59]
	v_mfma_f32_16x16x32_bf16 v[44:47], v[132:135], v[226:229], v[44:47]
	v_mfma_f32_16x16x32_bf16 v[40:43], v[140:143], v[226:229], v[40:43]
	v_mfma_f32_16x16x32_bf16 v[28:31], v[132:135], v[234:237], v[28:31]
	v_mfma_f32_16x16x32_bf16 v[24:27], v[140:143], v[234:237], v[24:27]
	v_mfma_f32_16x16x32_bf16 v[12:15], v[132:135], v[242:245], v[12:15]
	v_mfma_f32_16x16x32_bf16 v[8:11], v[140:143], v[242:245], v[8:11]
	v_mfma_f32_16x16x32_bf16 v[60:63], v[136:139], v[222:225], v[60:63]
	v_mfma_f32_16x16x32_bf16 v[56:59], v[180:183], v[222:225], v[56:59]
	v_mfma_f32_16x16x32_bf16 v[44:47], v[136:139], v[230:233], v[44:47]
	v_mfma_f32_16x16x32_bf16 v[40:43], v[180:183], v[230:233], v[40:43]
	v_mfma_f32_16x16x32_bf16 v[28:31], v[136:139], v[238:241], v[28:31]
	v_mfma_f32_16x16x32_bf16 v[24:27], v[180:183], v[238:241], v[24:27]
	v_mfma_f32_16x16x32_bf16 v[12:15], v[136:139], v[246:249], v[12:15]
	v_mfma_f32_16x16x32_bf16 v[8:11], v[180:183], v[246:249], v[8:11]
	s_setprio 0
	s_setprio 1
	v_mfma_f32_16x16x32_bf16 v[52:55], v[202:205], v[218:221], v[52:55]
	v_mfma_f32_16x16x32_bf16 v[48:51], v[210:213], v[218:221], v[48:51]
	v_mfma_f32_16x16x32_bf16 v[36:39], v[202:205], v[226:229], v[36:39]
	v_mfma_f32_16x16x32_bf16 v[32:35], v[210:213], v[226:229], v[32:35]
	v_mfma_f32_16x16x32_bf16 v[20:23], v[202:205], v[234:237], v[20:23]
	v_mfma_f32_16x16x32_bf16 v[16:19], v[210:213], v[234:237], v[16:19]
	v_mfma_f32_16x16x32_bf16 v[4:7], v[202:205], v[242:245], v[4:7]
	v_mfma_f32_16x16x32_bf16 v[0:3], v[210:213], v[242:245], v[0:3]
	v_mfma_f32_16x16x32_bf16 v[52:55], v[206:209], v[222:225], v[52:55]
	v_mfma_f32_16x16x32_bf16 v[48:51], v[214:217], v[222:225], v[48:51]
	v_mfma_f32_16x16x32_bf16 v[36:39], v[206:209], v[230:233], v[36:39]
	v_mfma_f32_16x16x32_bf16 v[32:35], v[214:217], v[230:233], v[32:35]
	v_mfma_f32_16x16x32_bf16 v[20:23], v[206:209], v[238:241], v[20:23]
	v_mfma_f32_16x16x32_bf16 v[16:19], v[214:217], v[238:241], v[16:19]
	v_mfma_f32_16x16x32_bf16 v[4:7], v[206:209], v[246:249], v[4:7]
	v_mfma_f32_16x16x32_bf16 v[0:3], v[214:217], v[246:249], v[0:3]
	s_barrier
	s_setprio 0
	s_add_i32 s58, s58, 2
	s_add_u32 s4, s4, 0x100
	s_addc_u32 s5, s5, 0
	s_add_u32 s56, s56, 0x100
	s_addc_u32 s57, s57, 0
	s_cmp_gt_u32 s58, 13
	s_cbranch_scc1 .LBB0_247

; #define PG8_STAGE(bufoff, gbase, voff) do { _Pragma("unroll") for (int _i = 0; _i < 2; ++_i) \
;         __builtin_amdgcn_global_load_lds((const unsigned*)((const char*)(gbase) + (voff)[_i]), (PG8_LAS unsigned*)(lds + (bufoff) + ldsw + _i * 8192), 16, 0, 0); } while (0)
; #define PG8_LDA(dst, b, h) do { _Pragma("unroll") for (int m = 0; m < 4; ++m) _Pragma("unroll") for (int k = 0; k < 2; ++k) dst[m][k] = *(const PG8_LAS bf16x8*)(lds + PG8_SA(b, h) + aoff + m * 2048 + k * 1024); } while (0)
; #define PG8_LDB(dst, b, h) do { _Pragma("unroll") for (int n = 0; n < 2; ++n) _Pragma("unroll") for (int k = 0; k < 2; ++k) dst[n][k] = *(const PG8_LAS bf16x8*)(lds + PG8_SB(b, h) + boff + n * 2048 + k * 1024); } while (0)
; template <class Epi, class Sched, bool ALIGN_EPI = false, bool SP2 = false>
; __device__ __forceinline__ void gemm_phase(PG8_LAS unsigned char* lds, const Gemm g, const Sched& S, const Epi& E) {
;     ...
;             const bool last = (t == nt - 2);
;             const char* a1 = cA + (size_t)(t + 1) * kstep;
;             const char* a2 = last ? nA : cA + (size_t)(t + 2) * kstep; const char* b2 = last ? nB : cB + (size_t)(t + 2) * kstep;
;             const char* a3 = a2 + kstep; const char* b3 = b2 + kstep;
;             if (last && has_next) S.a_ready(nxt);
;             if (last) E.pre(cur, wid, lane);
;             if constexpr (SP2) {
;             PG8_LDB(B0, 0, 0); PG8_LDB(B1, 0, 1); PG8_SCHED; PG8_LDA(At, 0, 0); PG8_STAGE(PG8_SA(1, 1), a1 + hstep, voffA);
;             PG8_WAIT_V(8); PG8_WAIT_L(0); PG8_BAR; PG8_MMA(0, 0, At, B0); PG8_MMA(0, 1, At, B1); PG8_BAR; PG8_SCHED;
;             PG8_LDA(At, 0, 1); PG8_STAGE(PG8_SB(0, 0), b2, voffB); PG8_STAGE(PG8_SB(0, 1), b2 + hstep, voffB); PG8_STAGE(PG8_SA(0, 0), a2, voffA);
;             PG8_WAIT_V(8); PG8_WAIT_L(0); PG8_BAR; PG8_MMA(1, 0, At, B0); PG8_MMA(1, 1, At, B1); PG8_BAR; PG8_SCHED;
;             PG8_LDB(B0, 1, 0); PG8_LDB(B1, 1, 1); PG8_SCHED; PG8_LDA(At, 1, 0); PG8_STAGE(PG8_SA(0, 1), a2 + hstep, voffA);
;             PG8_WAIT_V(8); PG8_WAIT_L(0); PG8_BAR; PG8_MMA(0, 0, At, B0); PG8_MMA(0, 1, At, B1); PG8_BAR; PG8_SCHED;
;             PG8_LDA(At, 1, 1); PG8_STAGE(PG8_SB(1, 0), b3, voffB); PG8_STAGE(PG8_SB(1, 1), b3 + hstep, voffB); PG8_STAGE(PG8_SA(1, 0), a3, voffA);
;             PG8_WAIT_V(8); PG8_WAIT_L(0); PG8_BAR; PG8_MMA(1, 0, At, B0); PG8_MMA(1, 1, At, B1); PG8_BAR; PG8_SCHED;
.LBB0_1562:
	s_add_u32 s0, s28, 0xfffc0080
	s_addc_u32 s1, s29, -1
	s_add_i32 s58, 0, 0x10000
	s_cmp_eq_u32 s57, 12
	s_cselect_b32 s7, s47, s1
	s_cselect_b32 s6, s53, s0
	s_cselect_b32 s1, s45, s56
	s_cselect_b32 s0, s54, s55
	s_add_i32 s60, 0, 0x14000
	v_add_u32_e32 v160, s58, v143
	v_add_u32_e32 v172, s60, v143
	ds_read_b128 v[138:141], v160
	ds_read_b128 v[152:155], v160 offset:1024
	ds_read_b128 v[156:159], v160 offset:2048
	ds_read_b128 v[160:163], v160 offset:3072
	ds_read_b128 v[164:167], v172
	ds_read_b128 v[168:171], v172 offset:1024
	ds_read_b128 v[180:183], v172 offset:2048
	ds_read_b128 v[198:201], v172 offset:3072
	v_lshl_add_u64 v[172:173], s[28:29], 0, v[134:135]
	s_add_i32 m0, s26, 0xc000
	ds_read_b128 v[202:205], v151
	ds_read_b128 v[206:209], v151 offset:1024
	ds_read_b128 v[210:213], v151 offset:2048
	ds_read_b128 v[214:217], v151 offset:3072
	ds_read_b128 v[218:221], v151 offset:4096
	ds_read_b128 v[222:225], v151 offset:5120
	ds_read_b128 v[226:229], v151 offset:6144
	ds_read_b128 v[230:233], v151 offset:7168
	global_load_lds_dwordx4 v[172:173], off
	v_lshl_add_u64 v[172:173], s[28:29], 0, v[136:137]
	s_add_i32 m0, s26, 0xe000
	s_nop 0
	global_load_lds_dwordx4 v[172:173], off
	s_waitcnt vmcnt(8)
	s_waitcnt lgkmcnt(0)
	s_setprio 1
	s_barrier
	v_mfma_f32_16x16x32_bf16 v[120:123], v[138:141], v[202:205], v[120:123]
	v_mfma_f32_16x16x32_bf16 v[124:127], v[156:159], v[202:205], v[124:127]
	v_mfma_f32_16x16x32_bf16 v[100:103], v[138:141], v[210:213], v[100:103]
	v_mfma_f32_16x16x32_bf16 v[104:107], v[156:159], v[210:213], v[104:107]
	v_mfma_f32_16x16x32_bf16 v[84:87], v[138:141], v[218:221], v[84:87]
	v_mfma_f32_16x16x32_bf16 v[88:91], v[156:159], v[218:221], v[88:91]
	v_mfma_f32_16x16x32_bf16 v[68:71], v[138:141], v[226:229], v[68:71]
	v_mfma_f32_16x16x32_bf16 v[72:75], v[156:159], v[226:229], v[72:75]
	v_mfma_f32_16x16x32_bf16 v[120:123], v[152:155], v[206:209], v[120:123]
	v_mfma_f32_16x16x32_bf16 v[124:127], v[160:163], v[206:209], v[124:127]
	v_mfma_f32_16x16x32_bf16 v[100:103], v[152:155], v[214:217], v[100:103]
	v_mfma_f32_16x16x32_bf16 v[104:107], v[160:163], v[214:217], v[104:107]
	v_mfma_f32_16x16x32_bf16 v[84:87], v[152:155], v[222:225], v[84:87]
	v_mfma_f32_16x16x32_bf16 v[88:91], v[160:163], v[222:225], v[88:91]
	v_mfma_f32_16x16x32_bf16 v[68:71], v[152:155], v[230:233], v[68:71]
	v_mfma_f32_16x16x32_bf16 v[72:75], v[160:163], v[230:233], v[72:75]
	s_setprio 0
	s_setprio 1
	v_mfma_f32_16x16x32_bf16 v[112:115], v[164:167], v[202:205], v[112:115]
	v_mfma_f32_16x16x32_bf16 v[116:119], v[180:183], v[202:205], v[116:119]
	v_mfma_f32_16x16x32_bf16 v[96:99], v[164:167], v[210:213], v[96:99]
	v_mfma_f32_16x16x32_bf16 v[108:111], v[180:183], v[210:213], v[108:111]
	v_mfma_f32_16x16x32_bf16 v[80:83], v[164:167], v[218:221], v[80:83]
	v_mfma_f32_16x16x32_bf16 v[92:95], v[180:183], v[218:221], v[92:95]
	v_mfma_f32_16x16x32_bf16 v[64:67], v[164:167], v[226:229], v[64:67]
	v_mfma_f32_16x16x32_bf16 v[76:79], v[180:183], v[226:229], v[76:79]
	v_mfma_f32_16x16x32_bf16 v[112:115], v[168:171], v[206:209], v[112:115]
	v_mfma_f32_16x16x32_bf16 v[116:119], v[198:201], v[206:209], v[116:119]
	v_mfma_f32_16x16x32_bf16 v[96:99], v[168:171], v[214:217], v[96:99]
	v_mfma_f32_16x16x32_bf16 v[108:111], v[198:201], v[214:217], v[108:111]
	v_mfma_f32_16x16x32_bf16 v[80:83], v[168:171], v[222:225], v[80:83]
	v_mfma_f32_16x16x32_bf16 v[92:95], v[198:201], v[222:225], v[92:95]
	v_mfma_f32_16x16x32_bf16 v[64:67], v[168:171], v[230:233], v[64:67]
	v_mfma_f32_16x16x32_bf16 v[76:79], v[198:201], v[230:233], v[76:79]
	s_barrier
	s_setprio 0
	s_add_i32 s58, s58, s25
	v_lshl_add_u64 v[172:173], s[0:1], 0, v[144:145]
	s_mov_b32 m0, s58
	ds_read_b128 v[202:205], v151 offset:16384
	ds_read_b128 v[206:209], v151 offset:17408
	ds_read_b128 v[210:213], v151 offset:18432
	ds_read_b128 v[214:217], v151 offset:19456
	ds_read_b128 v[218:221], v151 offset:20480
	ds_read_b128 v[222:225], v151 offset:21504
	ds_read_b128 v[226:229], v151 offset:22528
	ds_read_b128 v[230:233], v151 offset:23552
	global_load_lds_dwordx4 v[172:173], off
	s_add_i32 m0, s58, 0x2000
	s_add_u32 s58, s0, 0x40000
	v_lshl_add_u64 v[184:185], s[0:1], 0, v[128:129]
	s_addc_u32 s59, s1, 0
	s_add_i32 s60, s60, s25
	global_load_lds_dwordx4 v[184:185], off
	v_lshl_add_u64 v[186:187], s[58:59], 0, v[144:145]
	s_mov_b32 m0, s60
	v_lshl_add_u64 v[188:189], s[6:7], 0, v[130:131]
	global_load_lds_dwordx4 v[186:187], off
	v_lshl_add_u64 v[186:187], s[58:59], 0, v[128:129]
	s_add_i32 m0, s60, 0x2000
	s_nop 0
	global_load_lds_dwordx4 v[186:187], off
	v_lshl_add_u64 v[186:187], s[6:7], 0, v[132:133]
	s_mov_b32 m0, s26
	s_nop 0
	global_load_lds_dwordx4 v[186:187], off
	s_mov_b32 m0, s27
	s_nop 0
	global_load_lds_dwordx4 v[188:189], off
	s_waitcnt vmcnt(8)
	s_waitcnt lgkmcnt(0)
	s_setprio 1
	s_barrier
; #define PG8_STAGE(bufoff, gbase, voff) do { _Pragma("unroll") for (int _i = 0; _i < 2; ++_i) \
;         __builtin_amdgcn_global_load_lds((const unsigned*)((const char*)(gbase) + (voff)[_i]), (PG8_LAS unsigned*)(lds + (bufoff) + ldsw + _i * 8192), 16, 0, 0); } while (0)
; #define PG8_LDA(dst, b, h) do { _Pragma("unroll") for (int m = 0; m < 4; ++m) _Pragma("unroll") for (int k = 0; k < 2; ++k) dst[m][k] = *(const PG8_LAS bf16x8*)(lds + PG8_SA(b, h) + aoff + m * 2048 + k * 1024); } while (0)
; #define PG8_LDB(dst, b, h) do { _Pragma("unroll") for (int n = 0; n < 2; ++n) _Pragma("unroll") for (int k = 0; k < 2; ++k) dst[n][k] = *(const PG8_LAS bf16x8*)(lds + PG8_SB(b, h) + boff + n * 2048 + k * 1024); } while (0)
; #define PG8_MMA(ai, bj, At, Bt) do { __builtin_amdgcn_s_setprio(1); _Pragma("unroll") for (int m = 0; m < 4; ++m) _Pragma("unroll") for (int n = 0; n < 2; ++n) _Pragma("unroll") for (int k = 0; k < 2; ++k) \
;         acc[ai][bj][m][n] = __builtin_amdgcn_mfma_f32_16x16x32_bf16(Bt[n][k], At[m][k], acc[ai][bj][m][n], 0, 0, 0); __builtin_amdgcn_s_setprio(0); } while (0)
; #define PG8_WAIT_V(n) asm volatile("s_waitcnt vmcnt(" #n ")" ::: "memory")
; #define PG8_WAIT_L(n) asm volatile("s_waitcnt lgkmcnt(" #n ")" ::: "memory")
; #define PG8_BAR __builtin_amdgcn_s_barrier()
; #define PG8_SCHED __builtin_amdgcn_sched_barrier(0)
; template <class Epi, class Sched, bool ALIGN_EPI = false, bool SP2 = false>
; __device__ __forceinline__ void gemm_phase(PG8_LAS unsigned char* lds, const Gemm g, const Sched& S, const Epi& E) {
;     ...
;             PG8_WAIT_V(8); PG8_WAIT_L(0); PG8_BAR; PG8_MMA(1, 0, At, B0); PG8_MMA(1, 1, At, B1); PG8_BAR; PG8_SCHED;
;             PG8_LDB(B0, 1, 0); PG8_LDB(B1, 1, 1); PG8_SCHED; PG8_LDA(At, 1, 0); PG8_STAGE(PG8_SA(0, 1), a2 + hstep, voffA);
;             PG8_WAIT_V(8); PG8_WAIT_L(0); PG8_BAR; PG8_MMA(0, 0, At, B0); PG8_MMA(0, 1, At, B1); PG8_BAR; PG8_SCHED;
	v_mfma_f32_16x16x32_bf16 v[52:55], v[138:141], v[202:205], v[52:55]
	v_mfma_f32_16x16x32_bf16 v[56:59], v[156:159], v[202:205], v[56:59]
	v_mfma_f32_16x16x32_bf16 v[36:39], v[138:141], v[210:213], v[36:39]
	v_mfma_f32_16x16x32_bf16 v[40:43], v[156:159], v[210:213], v[40:43]
	v_mfma_f32_16x16x32_bf16 v[20:23], v[138:141], v[218:221], v[20:23]
	v_mfma_f32_16x16x32_bf16 v[24:27], v[156:159], v[218:221], v[24:27]
	v_mfma_f32_16x16x32_bf16 v[4:7], v[138:141], v[226:229], v[4:7]
	v_mfma_f32_16x16x32_bf16 v[8:11], v[156:159], v[226:229], v[8:11]
	v_mfma_f32_16x16x32_bf16 v[52:55], v[152:155], v[206:209], v[52:55]
	v_mfma_f32_16x16x32_bf16 v[56:59], v[160:163], v[206:209], v[56:59]
	v_mfma_f32_16x16x32_bf16 v[36:39], v[152:155], v[214:217], v[36:39]
	v_mfma_f32_16x16x32_bf16 v[40:43], v[160:163], v[214:217], v[40:43]
	v_mfma_f32_16x16x32_bf16 v[20:23], v[152:155], v[222:225], v[20:23]
	v_mfma_f32_16x16x32_bf16 v[24:27], v[160:163], v[222:225], v[24:27]
	v_mfma_f32_16x16x32_bf16 v[4:7], v[152:155], v[230:233], v[4:7]
	v_mfma_f32_16x16x32_bf16 v[8:11], v[160:163], v[230:233], v[8:11]
	s_setprio 0
	s_setprio 1
	v_mfma_f32_16x16x32_bf16 v[48:51], v[164:167], v[202:205], v[48:51]
	v_mfma_f32_16x16x32_bf16 v[60:63], v[180:183], v[202:205], v[60:63]
	v_mfma_f32_16x16x32_bf16 v[32:35], v[164:167], v[210:213], v[32:35]
	v_mfma_f32_16x16x32_bf16 v[44:47], v[180:183], v[210:213], v[44:47]
	v_mfma_f32_16x16x32_bf16 v[16:19], v[164:167], v[218:221], v[16:19]
	v_mfma_f32_16x16x32_bf16 v[28:31], v[180:183], v[218:221], v[28:31]
	v_mfma_f32_16x16x32_bf16 v[0:3], v[164:167], v[226:229], v[0:3]
	v_mfma_f32_16x16x32_bf16 v[12:15], v[180:183], v[226:229], v[12:15]
	v_mfma_f32_16x16x32_bf16 v[48:51], v[168:171], v[206:209], v[48:51]
	v_mfma_f32_16x16x32_bf16 v[60:63], v[198:201], v[206:209], v[60:63]
	v_mfma_f32_16x16x32_bf16 v[32:35], v[168:171], v[214:217], v[32:35]
	v_mfma_f32_16x16x32_bf16 v[44:47], v[198:201], v[214:217], v[44:47]
	v_mfma_f32_16x16x32_bf16 v[16:19], v[168:171], v[222:225], v[16:19]
	v_mfma_f32_16x16x32_bf16 v[28:31], v[198:201], v[222:225], v[28:31]
	v_mfma_f32_16x16x32_bf16 v[0:3], v[168:171], v[230:233], v[0:3]
	v_mfma_f32_16x16x32_bf16 v[12:15], v[198:201], v[230:233], v[12:15]
	s_barrier
	s_setprio 0
	s_add_i32 s58, 0, 0x18000
	s_add_i32 s59, 0, 0x1c000
	v_add_u32_e32 v160, s58, v143
	v_add_u32_e32 v190, s59, v143
	ds_read_b128 v[138:141], v160
	ds_read_b128 v[152:155], v160 offset:1024
	ds_read_b128 v[156:159], v160 offset:2048
	ds_read_b128 v[160:163], v160 offset:3072
	ds_read_b128 v[164:167], v190
	ds_read_b128 v[168:171], v190 offset:1024
	ds_read_b128 v[180:183], v190 offset:2048
	ds_read_b128 v[198:201], v190 offset:3072
	s_add_u32 s6, s6, 0x40000
	s_addc_u32 s7, s7, 0
	s_mov_b32 m0, s30
	v_lshl_add_u64 v[190:191], s[6:7], 0, v[132:133]
	ds_read_b128 v[202:205], v151 offset:32768
	ds_read_b128 v[206:209], v151 offset:33792
	ds_read_b128 v[210:213], v151 offset:34816
	ds_read_b128 v[214:217], v151 offset:35840
	ds_read_b128 v[218:221], v151 offset:36864
	ds_read_b128 v[222:225], v151 offset:37888
	ds_read_b128 v[226:229], v151 offset:38912
	ds_read_b128 v[230:233], v151 offset:39936
	global_load_lds_dwordx4 v[190:191], off
	v_lshl_add_u64 v[190:191], s[6:7], 0, v[130:131]
	s_mov_b32 m0, s31
	s_nop 0
	global_load_lds_dwordx4 v[190:191], off
	s_waitcnt vmcnt(8)
	s_waitcnt lgkmcnt(0)
	s_setprio 1
	s_barrier
	v_mfma_f32_16x16x32_bf16 v[120:123], v[138:141], v[202:205], v[120:123]
	v_mfma_f32_16x16x32_bf16 v[124:127], v[156:159], v[202:205], v[124:127]
	v_mfma_f32_16x16x32_bf16 v[100:103], v[138:141], v[210:213], v[100:103]
	v_mfma_f32_16x16x32_bf16 v[104:107], v[156:159], v[210:213], v[104:107]
	v_mfma_f32_16x16x32_bf16 v[84:87], v[138:141], v[218:221], v[84:87]
	v_mfma_f32_16x16x32_bf16 v[88:91], v[156:159], v[218:221], v[88:91]
	v_mfma_f32_16x16x32_bf16 v[68:71], v[138:141], v[226:229], v[68:71]
	v_mfma_f32_16x16x32_bf16 v[72:75], v[156:159], v[226:229], v[72:75]
	v_mfma_f32_16x16x32_bf16 v[120:123], v[152:155], v[206:209], v[120:123]
	v_mfma_f32_16x16x32_bf16 v[124:127], v[160:163], v[206:209], v[124:127]
	v_mfma_f32_16x16x32_bf16 v[100:103], v[152:155], v[214:217], v[100:103]
	v_mfma_f32_16x16x32_bf16 v[104:107], v[160:163], v[214:217], v[104:107]
	v_mfma_f32_16x16x32_bf16 v[84:87], v[152:155], v[222:225], v[84:87]
	v_mfma_f32_16x16x32_bf16 v[88:91], v[160:163], v[222:225], v[88:91]
	v_mfma_f32_16x16x32_bf16 v[68:71], v[152:155], v[230:233], v[68:71]
	v_mfma_f32_16x16x32_bf16 v[72:75], v[160:163], v[230:233], v[72:75]
	s_setprio 0
	s_setprio 1
	v_mfma_f32_16x16x32_bf16 v[112:115], v[164:167], v[202:205], v[112:115]
	v_mfma_f32_16x16x32_bf16 v[116:119], v[180:183], v[202:205], v[116:119]
	v_mfma_f32_16x16x32_bf16 v[96:99], v[164:167], v[210:213], v[96:99]
	v_mfma_f32_16x16x32_bf16 v[108:111], v[180:183], v[210:213], v[108:111]
	v_mfma_f32_16x16x32_bf16 v[80:83], v[164:167], v[218:221], v[80:83]
	v_mfma_f32_16x16x32_bf16 v[92:95], v[180:183], v[218:221], v[92:95]
	v_mfma_f32_16x16x32_bf16 v[64:67], v[164:167], v[226:229], v[64:67]
	v_mfma_f32_16x16x32_bf16 v[76:79], v[180:183], v[226:229], v[76:79]
	v_mfma_f32_16x16x32_bf16 v[112:115], v[168:171], v[206:209], v[112:115]
	v_mfma_f32_16x16x32_bf16 v[116:119], v[198:201], v[206:209], v[116:119]
	v_mfma_f32_16x16x32_bf16 v[96:99], v[168:171], v[214:217], v[96:99]
	v_mfma_f32_16x16x32_bf16 v[108:111], v[198:201], v[214:217], v[108:111]
	v_mfma_f32_16x16x32_bf16 v[80:83], v[168:171], v[222:225], v[80:83]
	v_mfma_f32_16x16x32_bf16 v[92:95], v[198:201], v[222:225], v[92:95]
	v_mfma_f32_16x16x32_bf16 v[64:67], v[168:171], v[230:233], v[64:67]
	v_mfma_f32_16x16x32_bf16 v[76:79], v[198:201], v[230:233], v[76:79]
	s_barrier
; #define PG8_STAGE(bufoff, gbase, voff) do { _Pragma("unroll") for (int _i = 0; _i < 2; ++_i) \
;         __builtin_amdgcn_global_load_lds((const unsigned*)((const char*)(gbase) + (voff)[_i]), (PG8_LAS unsigned*)(lds + (bufoff) + ldsw + _i * 8192), 16, 0, 0); } while (0)
; #define PG8_LDA(dst, b, h) do { _Pragma("unroll") for (int m = 0; m < 4; ++m) _Pragma("unroll") for (int k = 0; k < 2; ++k) dst[m][k] = *(const PG8_LAS bf16x8*)(lds + PG8_SA(b, h) + aoff + m * 2048 + k * 1024); } while (0)
; #define PG8_LDB(dst, b, h) do { _Pragma("unroll") for (int n = 0; n < 2; ++n) _Pragma("unroll") for (int k = 0; k < 2; ++k) dst[n][k] = *(const PG8_LAS bf16x8*)(lds + PG8_SB(b, h) + boff + n * 2048 + k * 1024); } while (0)
; #define PG8_MMA(ai, bj, At, Bt) do { __builtin_amdgcn_s_setprio(1); _Pragma("unroll") for (int m = 0; m < 4; ++m) _Pragma("unroll") for (int n = 0; n < 2; ++n) _Pragma("unroll") for (int k = 0; k < 2; ++k) \
;         acc[ai][bj][m][n] = __builtin_amdgcn_mfma_f32_16x16x32_bf16(Bt[n][k], At[m][k], acc[ai][bj][m][n], 0, 0, 0); __builtin_amdgcn_s_setprio(0); } while (0)
; #define PG8_WAIT_V(n) asm volatile("s_waitcnt vmcnt(" #n ")" ::: "memory")
; #define PG8_WAIT_L(n) asm volatile("s_waitcnt lgkmcnt(" #n ")" ::: "memory")
; #define PG8_BAR __builtin_amdgcn_s_barrier()
; #define PG8_SCHED __builtin_amdgcn_sched_barrier(0)
; template <class Epi, class Sched, bool ALIGN_EPI = false, bool SP2 = false>
; __device__ __forceinline__ void gemm_phase(PG8_LAS unsigned char* lds, const Gemm g, const Sched& S, const Epi& E) {
;     ...
;             PG8_LDB(B0, 1, 0); PG8_LDB(B1, 1, 1); PG8_SCHED; PG8_LDA(At, 1, 0); PG8_STAGE(PG8_SA(0, 1), a2 + hstep, voffA);
;             PG8_WAIT_V(8); PG8_WAIT_L(0); PG8_BAR; PG8_MMA(0, 0, At, B0); PG8_MMA(0, 1, At, B1); PG8_BAR; PG8_SCHED;
;             PG8_LDA(At, 1, 1); PG8_STAGE(PG8_SB(1, 0), b3, voffB); PG8_STAGE(PG8_SB(1, 1), b3 + hstep, voffB); PG8_STAGE(PG8_SA(1, 0), a3, voffA);
;             PG8_WAIT_V(8); PG8_WAIT_L(0); PG8_BAR; PG8_MMA(1, 0, At, B0); PG8_MMA(1, 1, At, B1); PG8_BAR; PG8_SCHED;
;     ...
;         if constexpr (ALIGN_EPI) { if (wr == 0) PG8_BAR; }
	s_setprio 0
	s_add_i32 s6, s58, s25
	v_lshl_add_u64 v[172:173], v[172:173], 0, s[94:95]
	s_mov_b32 m0, s6
	ds_read_b128 v[202:205], v151 offset:49152
	ds_read_b128 v[206:209], v151 offset:50176
	ds_read_b128 v[210:213], v151 offset:51200
	ds_read_b128 v[214:217], v151 offset:52224
	ds_read_b128 v[218:221], v151 offset:53248
	ds_read_b128 v[222:225], v151 offset:54272
	ds_read_b128 v[226:229], v151 offset:55296
	ds_read_b128 v[230:233], v151 offset:56320
	global_load_lds_dwordx4 v[172:173], off
	s_add_i32 m0, s6, 0x2000
	s_add_u32 s0, s0, 0x40080
	v_lshl_add_u64 v[172:173], v[184:185], 0, s[94:95]
	s_addc_u32 s1, s1, 0
	s_add_i32 s6, s59, s25
	global_load_lds_dwordx4 v[172:173], off
	v_lshl_add_u64 v[172:173], s[0:1], 0, v[144:145]
	s_mov_b32 m0, s6
	s_nop 0
	global_load_lds_dwordx4 v[172:173], off
	v_lshl_add_u64 v[172:173], s[0:1], 0, v[128:129]
	s_add_i32 m0, s6, 0x2000
	s_nop 0
	global_load_lds_dwordx4 v[172:173], off
	v_lshl_add_u64 v[172:173], v[186:187], 0, s[94:95]
	s_mov_b32 m0, s34
	s_nop 0
	global_load_lds_dwordx4 v[172:173], off
	v_lshl_add_u64 v[172:173], v[188:189], 0, s[94:95]
	s_mov_b32 m0, s35
	s_nop 0
	global_load_lds_dwordx4 v[172:173], off
	s_waitcnt vmcnt(8)
	s_waitcnt lgkmcnt(0)
	s_setprio 1
	s_barrier
	v_mfma_f32_16x16x32_bf16 v[52:55], v[138:141], v[202:205], v[52:55]
	v_mfma_f32_16x16x32_bf16 v[56:59], v[156:159], v[202:205], v[56:59]
	v_mfma_f32_16x16x32_bf16 v[36:39], v[138:141], v[210:213], v[36:39]
	v_mfma_f32_16x16x32_bf16 v[40:43], v[156:159], v[210:213], v[40:43]
	v_mfma_f32_16x16x32_bf16 v[20:23], v[138:141], v[218:221], v[20:23]
	v_mfma_f32_16x16x32_bf16 v[24:27], v[156:159], v[218:221], v[24:27]
	v_mfma_f32_16x16x32_bf16 v[4:7], v[138:141], v[226:229], v[4:7]
	v_mfma_f32_16x16x32_bf16 v[8:11], v[156:159], v[226:229], v[8:11]
	v_mfma_f32_16x16x32_bf16 v[52:55], v[152:155], v[206:209], v[52:55]
	v_mfma_f32_16x16x32_bf16 v[56:59], v[160:163], v[206:209], v[56:59]
	v_mfma_f32_16x16x32_bf16 v[36:39], v[152:155], v[214:217], v[36:39]
	v_mfma_f32_16x16x32_bf16 v[40:43], v[160:163], v[214:217], v[40:43]
	v_mfma_f32_16x16x32_bf16 v[20:23], v[152:155], v[222:225], v[20:23]
	v_mfma_f32_16x16x32_bf16 v[24:27], v[160:163], v[222:225], v[24:27]
	v_mfma_f32_16x16x32_bf16 v[4:7], v[152:155], v[230:233], v[4:7]
	v_mfma_f32_16x16x32_bf16 v[8:11], v[160:163], v[230:233], v[8:11]
	s_setprio 0
	s_setprio 1
	v_mfma_f32_16x16x32_bf16 v[48:51], v[164:167], v[202:205], v[48:51]
	v_mfma_f32_16x16x32_bf16 v[60:63], v[180:183], v[202:205], v[60:63]
	v_mfma_f32_16x16x32_bf16 v[32:35], v[164:167], v[210:213], v[32:35]
	v_mfma_f32_16x16x32_bf16 v[44:47], v[180:183], v[210:213], v[44:47]
	v_mfma_f32_16x16x32_bf16 v[16:19], v[164:167], v[218:221], v[16:19]
	v_mfma_f32_16x16x32_bf16 v[28:31], v[180:183], v[218:221], v[28:31]
	v_mfma_f32_16x16x32_bf16 v[0:3], v[164:167], v[226:229], v[0:3]
	v_mfma_f32_16x16x32_bf16 v[12:15], v[180:183], v[226:229], v[12:15]
	v_mfma_f32_16x16x32_bf16 v[48:51], v[168:171], v[206:209], v[48:51]
	v_mfma_f32_16x16x32_bf16 v[60:63], v[198:201], v[206:209], v[60:63]
	v_mfma_f32_16x16x32_bf16 v[32:35], v[168:171], v[214:217], v[32:35]
	v_mfma_f32_16x16x32_bf16 v[44:47], v[198:201], v[214:217], v[44:47]
	v_mfma_f32_16x16x32_bf16 v[16:19], v[168:171], v[222:225], v[16:19]
	v_mfma_f32_16x16x32_bf16 v[28:31], v[198:201], v[222:225], v[28:31]
	v_mfma_f32_16x16x32_bf16 v[0:3], v[168:171], v[230:233], v[0:3]
	v_mfma_f32_16x16x32_bf16 v[12:15], v[198:201], v[230:233], v[12:15]
	s_barrier
	s_setprio 0
	s_add_i32 s57, s57, 2
	s_add_u32 s28, s28, 0x100
	s_addc_u32 s29, s29, 0
	s_add_u32 s55, s55, 0x100
	s_addc_u32 s56, s56, 0
	s_cmp_gt_u32 s57, 13
	s_cbranch_scc0 .LBB0_1562
	s_and_b64 vcc, exec, s[42:43]
	s_cbranch_vccz .LBB0_1565
	s_barrier

; #define PG8_STAGE(bufoff, gbase, voff) do { _Pragma("unroll") for (int _i = 0; _i < 2; ++_i) \
;         __builtin_amdgcn_global_load_lds((const unsigned*)((const char*)(gbase) + (voff)[_i]), (PG8_LAS unsigned*)(lds + (bufoff) + ldsw + _i * 8192), 16, 0, 0); } while (0)
; #define PG8_LDA(dst, b, h) do { _Pragma("unroll") for (int m = 0; m < 4; ++m) _Pragma("unroll") for (int k = 0; k < 2; ++k) dst[m][k] = *(const PG8_LAS bf16x8*)(lds + PG8_SA(b, h) + aoff + m * 2048 + k * 1024); } while (0)
; #define PG8_LDB(dst, b, h) do { _Pragma("unroll") for (int n = 0; n < 2; ++n) _Pragma("unroll") for (int k = 0; k < 2; ++k) dst[n][k] = *(const PG8_LAS bf16x8*)(lds + PG8_SB(b, h) + boff + n * 2048 + k * 1024); } while (0)
; template <class Epi, class Sched, bool ALIGN_EPI = false, bool SP2 = false>
; __device__ __forceinline__ void gemm_phase(PG8_LAS unsigned char* lds, const Gemm g, const Sched& S, const Epi& E) {
;     ...
;             const bool last = (t == nt - 2);
;             const char* a1 = cA + (size_t)(t + 1) * kstep;
;             const char* a2 = last ? nA : cA + (size_t)(t + 2) * kstep; const char* b2 = last ? nB : cB + (size_t)(t + 2) * kstep;
;             const char* a3 = a2 + kstep; const char* b3 = b2 + kstep;
;             if (last && has_next) S.a_ready(nxt);
;             if (last) E.pre(cur, wid, lane);
;             if constexpr (SP2) {
;             PG8_LDB(B0, 0, 0); PG8_LDB(B1, 0, 1); PG8_SCHED; PG8_LDA(At, 0, 0); PG8_STAGE(PG8_SA(1, 1), a1 + hstep, voffA);
;             PG8_WAIT_V(8); PG8_WAIT_L(0); PG8_BAR; PG8_MMA(0, 0, At, B0); PG8_MMA(0, 1, At, B1); PG8_BAR; PG8_SCHED;
;             PG8_LDA(At, 0, 1); PG8_STAGE(PG8_SB(0, 0), b2, voffB); PG8_STAGE(PG8_SB(0, 1), b2 + hstep, voffB); PG8_STAGE(PG8_SA(0, 0), a2, voffA);
;             PG8_WAIT_V(8); PG8_WAIT_L(0); PG8_BAR; PG8_MMA(1, 0, At, B0); PG8_MMA(1, 1, At, B1); PG8_BAR; PG8_SCHED;
;             PG8_LDB(B0, 1, 0); PG8_LDB(B1, 1, 1); PG8_SCHED; PG8_LDA(At, 1, 0); PG8_STAGE(PG8_SA(0, 1), a2 + hstep, voffA);
;             PG8_WAIT_V(8); PG8_WAIT_L(0); PG8_BAR; PG8_MMA(0, 0, At, B0); PG8_MMA(0, 1, At, B1); PG8_BAR; PG8_SCHED;
;             PG8_LDA(At, 1, 1); PG8_STAGE(PG8_SB(1, 0), b3, voffB); PG8_STAGE(PG8_SB(1, 1), b3 + hstep, voffB); PG8_STAGE(PG8_SA(1, 0), a3, voffA);
;             PG8_WAIT_V(8); PG8_WAIT_L(0); PG8_BAR; PG8_MMA(1, 0, At, B0); PG8_MMA(1, 1, At, B1); PG8_BAR; PG8_SCHED;
.LBB0_1647:
	s_add_u32 s6, s4, 0xfffc0080
	s_addc_u32 s7, s5, -1
	s_and_b64 s[0:1], s[0:1], exec
	s_cselect_b32 s7, s39, s7
	s_cselect_b32 s6, s47, s6
	s_cselect_b32 s1, s53, s56
	s_cselect_b32 s0, s54, s55
	s_add_i32 s58, 0, 0x10000
	v_add_u32_e32 v162, s58, v165
	s_add_i32 s60, 0, 0x14000
	ds_read_b128 v[132:135], v162
	ds_read_b128 v[136:139], v162 offset:1024
	ds_read_b128 v[140:143], v162 offset:2048
	ds_read_b128 v[180:183], v162 offset:3072
	v_add_u32_e32 v162, s60, v165
	ds_read_b128 v[200:203], v162
	ds_read_b128 v[204:207], v162 offset:1024
	ds_read_b128 v[208:211], v162 offset:2048
	ds_read_b128 v[212:215], v162 offset:3072
	v_lshl_add_u64 v[168:169], s[4:5], 0, v[158:159]
	s_add_i32 m0, s27, 0xc000
	ds_read_b128 v[216:219], v197
	ds_read_b128 v[220:223], v197 offset:1024
	ds_read_b128 v[224:227], v197 offset:2048
	ds_read_b128 v[228:231], v197 offset:3072
	ds_read_b128 v[232:235], v197 offset:4096
	ds_read_b128 v[236:239], v197 offset:5120
	ds_read_b128 v[240:243], v197 offset:6144
	ds_read_b128 v[244:247], v197 offset:7168
	global_load_lds_dwordx4 v[168:169], off
	v_lshl_add_u64 v[168:169], s[4:5], 0, v[160:161]
	s_add_i32 m0, s27, 0xe000
	s_nop 0
	global_load_lds_dwordx4 v[168:169], off
	s_waitcnt vmcnt(8)
	s_waitcnt lgkmcnt(0)
	s_setprio 1
	s_barrier
	v_mfma_f32_16x16x32_bf16 v[124:127], v[132:135], v[216:219], v[124:127]
	v_mfma_f32_16x16x32_bf16 v[116:119], v[140:143], v[216:219], v[116:119]
	v_mfma_f32_16x16x32_bf16 v[108:111], v[132:135], v[224:227], v[108:111]
	v_mfma_f32_16x16x32_bf16 v[100:103], v[140:143], v[224:227], v[100:103]
	v_mfma_f32_16x16x32_bf16 v[92:95], v[132:135], v[232:235], v[92:95]
	v_mfma_f32_16x16x32_bf16 v[84:87], v[140:143], v[232:235], v[84:87]
	v_mfma_f32_16x16x32_bf16 v[76:79], v[132:135], v[240:243], v[76:79]
	v_mfma_f32_16x16x32_bf16 v[68:71], v[140:143], v[240:243], v[68:71]
	v_mfma_f32_16x16x32_bf16 v[124:127], v[136:139], v[220:223], v[124:127]
	v_mfma_f32_16x16x32_bf16 v[116:119], v[180:183], v[220:223], v[116:119]
	v_mfma_f32_16x16x32_bf16 v[108:111], v[136:139], v[228:231], v[108:111]
	v_mfma_f32_16x16x32_bf16 v[100:103], v[180:183], v[228:231], v[100:103]
	v_mfma_f32_16x16x32_bf16 v[92:95], v[136:139], v[236:239], v[92:95]
	v_mfma_f32_16x16x32_bf16 v[84:87], v[180:183], v[236:239], v[84:87]
	v_mfma_f32_16x16x32_bf16 v[76:79], v[136:139], v[244:247], v[76:79]
	v_mfma_f32_16x16x32_bf16 v[68:71], v[180:183], v[244:247], v[68:71]
	s_setprio 0
	s_setprio 1
	v_mfma_f32_16x16x32_bf16 v[120:123], v[200:203], v[216:219], v[120:123]
	v_mfma_f32_16x16x32_bf16 v[112:115], v[208:211], v[216:219], v[112:115]
	v_mfma_f32_16x16x32_bf16 v[104:107], v[200:203], v[224:227], v[104:107]
	v_mfma_f32_16x16x32_bf16 v[96:99], v[208:211], v[224:227], v[96:99]
	v_mfma_f32_16x16x32_bf16 v[88:91], v[200:203], v[232:235], v[88:91]
	v_mfma_f32_16x16x32_bf16 v[80:83], v[208:211], v[232:235], v[80:83]
	v_mfma_f32_16x16x32_bf16 v[72:75], v[200:203], v[240:243], v[72:75]
	v_mfma_f32_16x16x32_bf16 v[64:67], v[208:211], v[240:243], v[64:67]
	v_mfma_f32_16x16x32_bf16 v[120:123], v[204:207], v[220:223], v[120:123]
	v_mfma_f32_16x16x32_bf16 v[112:115], v[212:215], v[220:223], v[112:115]
	v_mfma_f32_16x16x32_bf16 v[104:107], v[204:207], v[228:231], v[104:107]
	v_mfma_f32_16x16x32_bf16 v[96:99], v[212:215], v[228:231], v[96:99]
	v_mfma_f32_16x16x32_bf16 v[88:91], v[204:207], v[236:239], v[88:91]
	v_mfma_f32_16x16x32_bf16 v[80:83], v[212:215], v[236:239], v[80:83]
	v_mfma_f32_16x16x32_bf16 v[72:75], v[204:207], v[244:247], v[72:75]
	v_mfma_f32_16x16x32_bf16 v[64:67], v[212:215], v[244:247], v[64:67]
	s_barrier
	s_setprio 0
	s_add_i32 s58, s58, s26
	v_lshl_add_u64 v[168:169], s[0:1], 0, v[144:145]
	s_mov_b32 m0, s58
	ds_read_b128 v[216:219], v197 offset:16384
	ds_read_b128 v[220:223], v197 offset:17408
	ds_read_b128 v[224:227], v197 offset:18432
	ds_read_b128 v[228:231], v197 offset:19456
	ds_read_b128 v[232:235], v197 offset:20480
	ds_read_b128 v[236:239], v197 offset:21504
	ds_read_b128 v[240:243], v197 offset:22528
	ds_read_b128 v[244:247], v197 offset:23552
	global_load_lds_dwordx4 v[168:169], off
	s_add_i32 m0, s58, 0x2000
	s_add_u32 s58, s0, 0x40000
	v_lshl_add_u64 v[172:173], s[0:1], 0, v[150:151]
	s_addc_u32 s59, s1, 0
	s_add_i32 s60, s60, s26
	global_load_lds_dwordx4 v[172:173], off
	v_lshl_add_u64 v[184:185], s[58:59], 0, v[144:145]
	s_mov_b32 m0, s60
	v_lshl_add_u64 v[186:187], s[6:7], 0, v[152:153]
	global_load_lds_dwordx4 v[184:185], off
	v_lshl_add_u64 v[184:185], s[58:59], 0, v[150:151]
	s_add_i32 m0, s60, 0x2000
	s_nop 0
	global_load_lds_dwordx4 v[184:185], off
	v_lshl_add_u64 v[184:185], s[6:7], 0, v[154:155]
	s_mov_b32 m0, s27
	s_nop 0
	global_load_lds_dwordx4 v[184:185], off
	s_mov_b32 m0, s28
	s_nop 0
	global_load_lds_dwordx4 v[186:187], off
	s_waitcnt vmcnt(8)
	s_waitcnt lgkmcnt(0)
	s_setprio 1
	s_barrier
; #define PG8_STAGE(bufoff, gbase, voff) do { _Pragma("unroll") for (int _i = 0; _i < 2; ++_i) \
;         __builtin_amdgcn_global_load_lds((const unsigned*)((const char*)(gbase) + (voff)[_i]), (PG8_LAS unsigned*)(lds + (bufoff) + ldsw + _i * 8192), 16, 0, 0); } while (0)
; #define PG8_LDA(dst, b, h) do { _Pragma("unroll") for (int m = 0; m < 4; ++m) _Pragma("unroll") for (int k = 0; k < 2; ++k) dst[m][k] = *(const PG8_LAS bf16x8*)(lds + PG8_SA(b, h) + aoff + m * 2048 + k * 1024); } while (0)
; #define PG8_LDB(dst, b, h) do { _Pragma("unroll") for (int n = 0; n < 2; ++n) _Pragma("unroll") for (int k = 0; k < 2; ++k) dst[n][k] = *(const PG8_LAS bf16x8*)(lds + PG8_SB(b, h) + boff + n * 2048 + k * 1024); } while (0)
; #define PG8_MMA(ai, bj, At, Bt) do { __builtin_amdgcn_s_setprio(1); _Pragma("unroll") for (int m = 0; m < 4; ++m) _Pragma("unroll") for (int n = 0; n < 2; ++n) _Pragma("unroll") for (int k = 0; k < 2; ++k) \
;         acc[ai][bj][m][n] = __builtin_amdgcn_mfma_f32_16x16x32_bf16(Bt[n][k], At[m][k], acc[ai][bj][m][n], 0, 0, 0); __builtin_amdgcn_s_setprio(0); } while (0)
; #define PG8_WAIT_V(n) asm volatile("s_waitcnt vmcnt(" #n ")" ::: "memory")
; #define PG8_WAIT_L(n) asm volatile("s_waitcnt lgkmcnt(" #n ")" ::: "memory")
; #define PG8_BAR __builtin_amdgcn_s_barrier()
; #define PG8_SCHED __builtin_amdgcn_sched_barrier(0)
; template <class Epi, class Sched, bool ALIGN_EPI = false, bool SP2 = false>
; __device__ __forceinline__ void gemm_phase(PG8_LAS unsigned char* lds, const Gemm g, const Sched& S, const Epi& E) {
;     ...
;             PG8_WAIT_V(8); PG8_WAIT_L(0); PG8_BAR; PG8_MMA(1, 0, At, B0); PG8_MMA(1, 1, At, B1); PG8_BAR; PG8_SCHED;
;             PG8_LDB(B0, 1, 0); PG8_LDB(B1, 1, 1); PG8_SCHED; PG8_LDA(At, 1, 0); PG8_STAGE(PG8_SA(0, 1), a2 + hstep, voffA);
;             PG8_WAIT_V(8); PG8_WAIT_L(0); PG8_BAR; PG8_MMA(0, 0, At, B0); PG8_MMA(0, 1, At, B1); PG8_BAR; PG8_SCHED;
	v_mfma_f32_16x16x32_bf16 v[60:63], v[132:135], v[216:219], v[60:63]
	v_mfma_f32_16x16x32_bf16 v[52:55], v[140:143], v[216:219], v[52:55]
	v_mfma_f32_16x16x32_bf16 v[44:47], v[132:135], v[224:227], v[44:47]
	v_mfma_f32_16x16x32_bf16 v[36:39], v[140:143], v[224:227], v[36:39]
	v_mfma_f32_16x16x32_bf16 v[28:31], v[132:135], v[232:235], v[28:31]
	v_mfma_f32_16x16x32_bf16 v[20:23], v[140:143], v[232:235], v[20:23]
	v_mfma_f32_16x16x32_bf16 v[12:15], v[132:135], v[240:243], v[12:15]
	v_mfma_f32_16x16x32_bf16 v[4:7], v[140:143], v[240:243], v[4:7]
	v_mfma_f32_16x16x32_bf16 v[60:63], v[136:139], v[220:223], v[60:63]
	v_mfma_f32_16x16x32_bf16 v[52:55], v[180:183], v[220:223], v[52:55]
	v_mfma_f32_16x16x32_bf16 v[44:47], v[136:139], v[228:231], v[44:47]
	v_mfma_f32_16x16x32_bf16 v[36:39], v[180:183], v[228:231], v[36:39]
	v_mfma_f32_16x16x32_bf16 v[28:31], v[136:139], v[236:239], v[28:31]
	v_mfma_f32_16x16x32_bf16 v[20:23], v[180:183], v[236:239], v[20:23]
	v_mfma_f32_16x16x32_bf16 v[12:15], v[136:139], v[244:247], v[12:15]
	v_mfma_f32_16x16x32_bf16 v[4:7], v[180:183], v[244:247], v[4:7]
	s_setprio 0
	s_setprio 1
	v_mfma_f32_16x16x32_bf16 v[56:59], v[200:203], v[216:219], v[56:59]
	v_mfma_f32_16x16x32_bf16 v[48:51], v[208:211], v[216:219], v[48:51]
	v_mfma_f32_16x16x32_bf16 v[40:43], v[200:203], v[224:227], v[40:43]
	v_mfma_f32_16x16x32_bf16 v[32:35], v[208:211], v[224:227], v[32:35]
	v_mfma_f32_16x16x32_bf16 v[24:27], v[200:203], v[232:235], v[24:27]
	v_mfma_f32_16x16x32_bf16 v[16:19], v[208:211], v[232:235], v[16:19]
	v_mfma_f32_16x16x32_bf16 v[8:11], v[200:203], v[240:243], v[8:11]
	v_mfma_f32_16x16x32_bf16 v[0:3], v[208:211], v[240:243], v[0:3]
	v_mfma_f32_16x16x32_bf16 v[56:59], v[204:207], v[220:223], v[56:59]
	v_mfma_f32_16x16x32_bf16 v[48:51], v[212:215], v[220:223], v[48:51]
	v_mfma_f32_16x16x32_bf16 v[40:43], v[204:207], v[228:231], v[40:43]
	v_mfma_f32_16x16x32_bf16 v[32:35], v[212:215], v[228:231], v[32:35]
	v_mfma_f32_16x16x32_bf16 v[24:27], v[204:207], v[236:239], v[24:27]
	v_mfma_f32_16x16x32_bf16 v[16:19], v[212:215], v[236:239], v[16:19]
	v_mfma_f32_16x16x32_bf16 v[8:11], v[204:207], v[244:247], v[8:11]
	v_mfma_f32_16x16x32_bf16 v[0:3], v[212:215], v[244:247], v[0:3]
	s_barrier
	s_setprio 0
	s_add_i32 s58, 0, 0x18000
	v_add_u32_e32 v162, s58, v165
	s_add_i32 s59, 0, 0x1c000
	ds_read_b128 v[132:135], v162
	ds_read_b128 v[136:139], v162 offset:1024
	ds_read_b128 v[140:143], v162 offset:2048
	ds_read_b128 v[180:183], v162 offset:3072
	v_add_u32_e32 v162, s59, v165
	ds_read_b128 v[200:203], v162
	ds_read_b128 v[204:207], v162 offset:1024
	ds_read_b128 v[208:211], v162 offset:2048
	ds_read_b128 v[212:215], v162 offset:3072
	s_add_u32 s6, s6, 0x40000
	s_addc_u32 s7, s7, 0
	s_mov_b32 m0, s29
	v_lshl_add_u64 v[188:189], s[6:7], 0, v[154:155]
	ds_read_b128 v[216:219], v197 offset:32768
	ds_read_b128 v[220:223], v197 offset:33792
	ds_read_b128 v[224:227], v197 offset:34816
	ds_read_b128 v[228:231], v197 offset:35840
	ds_read_b128 v[232:235], v197 offset:36864
	ds_read_b128 v[236:239], v197 offset:37888
	ds_read_b128 v[240:243], v197 offset:38912
	ds_read_b128 v[244:247], v197 offset:39936
	global_load_lds_dwordx4 v[188:189], off
	v_lshl_add_u64 v[188:189], s[6:7], 0, v[152:153]
	s_mov_b32 m0, s30
	s_nop 0
	global_load_lds_dwordx4 v[188:189], off
	s_waitcnt vmcnt(8)
	s_waitcnt lgkmcnt(0)
	s_setprio 1
	s_barrier
	v_mfma_f32_16x16x32_bf16 v[124:127], v[132:135], v[216:219], v[124:127]
	v_mfma_f32_16x16x32_bf16 v[116:119], v[140:143], v[216:219], v[116:119]
	v_mfma_f32_16x16x32_bf16 v[108:111], v[132:135], v[224:227], v[108:111]
	v_mfma_f32_16x16x32_bf16 v[100:103], v[140:143], v[224:227], v[100:103]
	v_mfma_f32_16x16x32_bf16 v[92:95], v[132:135], v[232:235], v[92:95]
	v_mfma_f32_16x16x32_bf16 v[84:87], v[140:143], v[232:235], v[84:87]
	v_mfma_f32_16x16x32_bf16 v[76:79], v[132:135], v[240:243], v[76:79]
	v_mfma_f32_16x16x32_bf16 v[68:71], v[140:143], v[240:243], v[68:71]
	v_mfma_f32_16x16x32_bf16 v[124:127], v[136:139], v[220:223], v[124:127]
	v_mfma_f32_16x16x32_bf16 v[116:119], v[180:183], v[220:223], v[116:119]
	v_mfma_f32_16x16x32_bf16 v[108:111], v[136:139], v[228:231], v[108:111]
	v_mfma_f32_16x16x32_bf16 v[100:103], v[180:183], v[228:231], v[100:103]
	v_mfma_f32_16x16x32_bf16 v[92:95], v[136:139], v[236:239], v[92:95]
	v_mfma_f32_16x16x32_bf16 v[84:87], v[180:183], v[236:239], v[84:87]
	v_mfma_f32_16x16x32_bf16 v[76:79], v[136:139], v[244:247], v[76:79]
	v_mfma_f32_16x16x32_bf16 v[68:71], v[180:183], v[244:247], v[68:71]
	s_setprio 0
	s_setprio 1
	v_mfma_f32_16x16x32_bf16 v[120:123], v[200:203], v[216:219], v[120:123]
	v_mfma_f32_16x16x32_bf16 v[112:115], v[208:211], v[216:219], v[112:115]
	v_mfma_f32_16x16x32_bf16 v[104:107], v[200:203], v[224:227], v[104:107]
	v_mfma_f32_16x16x32_bf16 v[96:99], v[208:211], v[224:227], v[96:99]
	v_mfma_f32_16x16x32_bf16 v[88:91], v[200:203], v[232:235], v[88:91]
	v_mfma_f32_16x16x32_bf16 v[80:83], v[208:211], v[232:235], v[80:83]
	v_mfma_f32_16x16x32_bf16 v[72:75], v[200:203], v[240:243], v[72:75]
	v_mfma_f32_16x16x32_bf16 v[64:67], v[208:211], v[240:243], v[64:67]
	v_mfma_f32_16x16x32_bf16 v[120:123], v[204:207], v[220:223], v[120:123]
	v_mfma_f32_16x16x32_bf16 v[112:115], v[212:215], v[220:223], v[112:115]
	v_mfma_f32_16x16x32_bf16 v[104:107], v[204:207], v[228:231], v[104:107]
	v_mfma_f32_16x16x32_bf16 v[96:99], v[212:215], v[228:231], v[96:99]
	v_mfma_f32_16x16x32_bf16 v[88:91], v[204:207], v[236:239], v[88:91]
	v_mfma_f32_16x16x32_bf16 v[80:83], v[212:215], v[236:239], v[80:83]
	v_mfma_f32_16x16x32_bf16 v[72:75], v[204:207], v[244:247], v[72:75]
	v_mfma_f32_16x16x32_bf16 v[64:67], v[212:215], v[244:247], v[64:67]
	s_barrier
; #define PG8_STAGE(bufoff, gbase, voff) do { _Pragma("unroll") for (int _i = 0; _i < 2; ++_i) \
;         __builtin_amdgcn_global_load_lds((const unsigned*)((const char*)(gbase) + (voff)[_i]), (PG8_LAS unsigned*)(lds + (bufoff) + ldsw + _i * 8192), 16, 0, 0); } while (0)
; #define PG8_LDA(dst, b, h) do { _Pragma("unroll") for (int m = 0; m < 4; ++m) _Pragma("unroll") for (int k = 0; k < 2; ++k) dst[m][k] = *(const PG8_LAS bf16x8*)(lds + PG8_SA(b, h) + aoff + m * 2048 + k * 1024); } while (0)
; #define PG8_WAIT_V(n) asm volatile("s_waitcnt vmcnt(" #n ")" ::: "memory")
; #define PG8_WAIT_L(n) asm volatile("s_waitcnt lgkmcnt(" #n ")" ::: "memory")
; template <class Epi, class Sched, bool ALIGN_EPI = false, bool SP2 = false>
; __device__ __forceinline__ void gemm_phase(PG8_LAS unsigned char* lds, const Gemm g, const Sched& S, const Epi& E) {
;     ...
;         for (int t = 0; t < nt; t += 2) {
;             const bool last = (t == nt - 2);
;             const char* a1 = cA + (size_t)(t + 1) * kstep;
;             const char* a2 = last ? nA : cA + (size_t)(t + 2) * kstep; const char* b2 = last ? nB : cB + (size_t)(t + 2) * kstep;
;             const char* a3 = a2 + kstep; const char* b3 = b2 + kstep;
;             if (last && has_next) S.a_ready(nxt);
;             if (last) E.pre(cur, wid, lane);
;             if constexpr (SP2) {
;             PG8_LDB(B0, 0, 0); PG8_LDB(B1, 0, 1); PG8_SCHED; PG8_LDA(At, 0, 0); PG8_STAGE(PG8_SA(1, 1), a1 + hstep, voffA);
;             PG8_WAIT_V(8); PG8_WAIT_L(0); PG8_BAR; PG8_MMA(0, 0, At, B0); PG8_MMA(0, 1, At, B1); PG8_BAR; PG8_SCHED;
;             PG8_LDA(At, 0, 1); PG8_STAGE(PG8_SB(0, 0), b2, voffB); PG8_STAGE(PG8_SB(0, 1), b2 + hstep, voffB); PG8_STAGE(PG8_SA(0, 0), a2, voffA);
;             PG8_WAIT_V(8); PG8_WAIT_L(0); PG8_BAR; PG8_MMA(1, 0, At, B0); PG8_MMA(1, 1, At, B1); PG8_BAR; PG8_SCHED;
;             PG8_LDB(B0, 1, 0); PG8_LDB(B1, 1, 1); PG8_SCHED; PG8_LDA(At, 1, 0); PG8_STAGE(PG8_SA(0, 1), a2 + hstep, voffA);
;             PG8_WAIT_V(8); PG8_WAIT_L(0); PG8_BAR; PG8_MMA(0, 0, At, B0); PG8_MMA(0, 1, At, B1); PG8_BAR; PG8_SCHED;
;             PG8_LDA(At, 1, 1); PG8_STAGE(PG8_SB(1, 0), b3, voffB); PG8_STAGE(PG8_SB(1, 1), b3 + hstep, voffB); PG8_STAGE(PG8_SA(1, 0), a3, voffA);
;             PG8_WAIT_V(8); PG8_WAIT_L(0); PG8_BAR; PG8_MMA(1, 0, At, B0); PG8_MMA(1, 1, At, B1); PG8_BAR; PG8_SCHED;
	s_setprio 0
	s_add_i32 s6, s58, s26
	v_lshl_add_u64 v[168:169], v[168:169], 0, s[94:95]
	s_mov_b32 m0, s6
	ds_read_b128 v[216:219], v197 offset:49152
	ds_read_b128 v[220:223], v197 offset:50176
	ds_read_b128 v[224:227], v197 offset:51200
	ds_read_b128 v[228:231], v197 offset:52224
	ds_read_b128 v[232:235], v197 offset:53248
	ds_read_b128 v[236:239], v197 offset:54272
	ds_read_b128 v[240:243], v197 offset:55296
	ds_read_b128 v[244:247], v197 offset:56320
	global_load_lds_dwordx4 v[168:169], off
	s_add_i32 m0, s6, 0x2000
	s_add_u32 s0, s0, 0x40080
	v_lshl_add_u64 v[168:169], v[172:173], 0, s[94:95]
	s_addc_u32 s1, s1, 0
	s_add_i32 s6, s59, s26
	global_load_lds_dwordx4 v[168:169], off
	v_lshl_add_u64 v[168:169], s[0:1], 0, v[144:145]
	s_mov_b32 m0, s6
	s_nop 0
	global_load_lds_dwordx4 v[168:169], off
	v_lshl_add_u64 v[168:169], s[0:1], 0, v[150:151]
	s_add_i32 m0, s6, 0x2000
	s_nop 0
	global_load_lds_dwordx4 v[168:169], off
	v_lshl_add_u64 v[168:169], v[184:185], 0, s[94:95]
	s_mov_b32 m0, s31
	s_nop 0
	global_load_lds_dwordx4 v[168:169], off
	v_lshl_add_u64 v[168:169], v[186:187], 0, s[94:95]
	s_mov_b32 m0, s34
	s_nop 0
	global_load_lds_dwordx4 v[168:169], off
	s_waitcnt vmcnt(8)
	s_waitcnt lgkmcnt(0)
	s_setprio 1
	s_barrier
	v_mfma_f32_16x16x32_bf16 v[60:63], v[132:135], v[216:219], v[60:63]
	v_mfma_f32_16x16x32_bf16 v[52:55], v[140:143], v[216:219], v[52:55]
	v_mfma_f32_16x16x32_bf16 v[44:47], v[132:135], v[224:227], v[44:47]
	v_mfma_f32_16x16x32_bf16 v[36:39], v[140:143], v[224:227], v[36:39]
	v_mfma_f32_16x16x32_bf16 v[28:31], v[132:135], v[232:235], v[28:31]
	v_mfma_f32_16x16x32_bf16 v[20:23], v[140:143], v[232:235], v[20:23]
	v_mfma_f32_16x16x32_bf16 v[12:15], v[132:135], v[240:243], v[12:15]
	v_mfma_f32_16x16x32_bf16 v[4:7], v[140:143], v[240:243], v[4:7]
	v_mfma_f32_16x16x32_bf16 v[60:63], v[136:139], v[220:223], v[60:63]
	v_mfma_f32_16x16x32_bf16 v[52:55], v[180:183], v[220:223], v[52:55]
	v_mfma_f32_16x16x32_bf16 v[44:47], v[136:139], v[228:231], v[44:47]
	v_mfma_f32_16x16x32_bf16 v[36:39], v[180:183], v[228:231], v[36:39]
	v_mfma_f32_16x16x32_bf16 v[28:31], v[136:139], v[236:239], v[28:31]
	v_mfma_f32_16x16x32_bf16 v[20:23], v[180:183], v[236:239], v[20:23]
	v_mfma_f32_16x16x32_bf16 v[12:15], v[136:139], v[244:247], v[12:15]
	v_mfma_f32_16x16x32_bf16 v[4:7], v[180:183], v[244:247], v[4:7]
	s_setprio 0
	s_setprio 1
	v_mfma_f32_16x16x32_bf16 v[56:59], v[200:203], v[216:219], v[56:59]
	v_mfma_f32_16x16x32_bf16 v[48:51], v[208:211], v[216:219], v[48:51]
	v_mfma_f32_16x16x32_bf16 v[40:43], v[200:203], v[224:227], v[40:43]
	v_mfma_f32_16x16x32_bf16 v[32:35], v[208:211], v[224:227], v[32:35]
	v_mfma_f32_16x16x32_bf16 v[24:27], v[200:203], v[232:235], v[24:27]
	v_mfma_f32_16x16x32_bf16 v[16:19], v[208:211], v[232:235], v[16:19]
	v_mfma_f32_16x16x32_bf16 v[8:11], v[200:203], v[240:243], v[8:11]
	v_mfma_f32_16x16x32_bf16 v[0:3], v[208:211], v[240:243], v[0:3]
	v_mfma_f32_16x16x32_bf16 v[56:59], v[204:207], v[220:223], v[56:59]
	v_mfma_f32_16x16x32_bf16 v[48:51], v[212:215], v[220:223], v[48:51]
	v_mfma_f32_16x16x32_bf16 v[40:43], v[204:207], v[228:231], v[40:43]
	v_mfma_f32_16x16x32_bf16 v[32:35], v[212:215], v[228:231], v[32:35]
	v_mfma_f32_16x16x32_bf16 v[24:27], v[204:207], v[236:239], v[24:27]
	v_mfma_f32_16x16x32_bf16 v[16:19], v[212:215], v[236:239], v[16:19]
	v_mfma_f32_16x16x32_bf16 v[8:11], v[204:207], v[244:247], v[8:11]
	v_mfma_f32_16x16x32_bf16 v[0:3], v[212:215], v[244:247], v[0:3]
	s_barrier
	s_setprio 0
	s_add_i32 s57, s57, 2
	s_add_u32 s4, s4, 0x100
	s_addc_u32 s5, s5, 0
	s_add_u32 s55, s55, 0x100
	s_addc_u32 s56, s56, 0
	s_cmp_gt_u32 s57, 13
	s_cbranch_scc1 .LBB0_1650

; #define PG8_STAGE(bufoff, gbase, voff) do { _Pragma("unroll") for (int _i = 0; _i < 2; ++_i) \
;         __builtin_amdgcn_global_load_lds((const unsigned*)((const char*)(gbase) + (voff)[_i]), (PG8_LAS unsigned*)(lds + (bufoff) + ldsw + _i * 8192), 16, 0, 0); } while (0)
; #define PG8_LDA(dst, b, h) do { _Pragma("unroll") for (int m = 0; m < 4; ++m) _Pragma("unroll") for (int k = 0; k < 2; ++k) dst[m][k] = *(const PG8_LAS bf16x8*)(lds + PG8_SA(b, h) + aoff + m * 2048 + k * 1024); } while (0)
; #define PG8_LDB(dst, b, h) do { _Pragma("unroll") for (int n = 0; n < 2; ++n) _Pragma("unroll") for (int k = 0; k < 2; ++k) dst[n][k] = *(const PG8_LAS bf16x8*)(lds + PG8_SB(b, h) + boff + n * 2048 + k * 1024); } while (0)
; template <class Epi, class Sched, bool ALIGN_EPI = false, bool SP2 = false>
; __device__ __forceinline__ void gemm_phase(PG8_LAS unsigned char* lds, const Gemm g, const Sched& S, const Epi& E) {
;     ...
;             const bool last = (t == nt - 2);
;             const char* a1 = cA + (size_t)(t + 1) * kstep;
;             const char* a2 = last ? nA : cA + (size_t)(t + 2) * kstep; const char* b2 = last ? nB : cB + (size_t)(t + 2) * kstep;
;             const char* a3 = a2 + kstep; const char* b3 = b2 + kstep;
;             if (last && has_next) S.a_ready(nxt);
;             if (last) E.pre(cur, wid, lane);
;             if constexpr (SP2) {
;             PG8_LDB(B0, 0, 0); PG8_LDB(B1, 0, 1); PG8_SCHED; PG8_LDA(At, 0, 0); PG8_STAGE(PG8_SA(1, 1), a1 + hstep, voffA);
;             PG8_WAIT_V(8); PG8_WAIT_L(0); PG8_BAR; PG8_MMA(0, 0, At, B0); PG8_MMA(0, 1, At, B1); PG8_BAR; PG8_SCHED;
;             PG8_LDA(At, 0, 1); PG8_STAGE(PG8_SB(0, 0), b2, voffB); PG8_STAGE(PG8_SB(0, 1), b2 + hstep, voffB); PG8_STAGE(PG8_SA(0, 0), a2, voffA);
;             PG8_WAIT_V(8); PG8_WAIT_L(0); PG8_BAR; PG8_MMA(1, 0, At, B0); PG8_MMA(1, 1, At, B1); PG8_BAR; PG8_SCHED;
;             PG8_LDB(B0, 1, 0); PG8_LDB(B1, 1, 1); PG8_SCHED; PG8_LDA(At, 1, 0); PG8_STAGE(PG8_SA(0, 1), a2 + hstep, voffA);
;             PG8_WAIT_V(8); PG8_WAIT_L(0); PG8_BAR; PG8_MMA(0, 0, At, B0); PG8_MMA(0, 1, At, B1); PG8_BAR; PG8_SCHED;
;             PG8_LDA(At, 1, 1); PG8_STAGE(PG8_SB(1, 0), b3, voffB); PG8_STAGE(PG8_SB(1, 1), b3 + hstep, voffB); PG8_STAGE(PG8_SA(1, 0), a3, voffA);
;             PG8_WAIT_V(8); PG8_WAIT_L(0); PG8_BAR; PG8_MMA(1, 0, At, B0); PG8_MMA(1, 1, At, B1); PG8_BAR; PG8_SCHED;
.LBB0_1900:
	s_add_u32 s0, s6, 0x100
	s_addc_u32 s1, s7, 0
	s_add_i32 s60, 0, 0x10000
	s_cmp_eq_u32 s59, 40
	s_cselect_b32 s25, s41, s1
	s_cselect_b32 s24, s40, s0
	s_cselect_b32 s5, s49, s58
	s_cselect_b32 s4, s48, s57
	s_add_i32 s61, 0, 0x14000
	v_add_u32_e32 v160, s60, v143
	v_add_u32_e32 v172, s61, v143
	ds_read_b128 v[138:141], v160
	ds_read_b128 v[152:155], v160 offset:1024
	ds_read_b128 v[156:159], v160 offset:2048
	ds_read_b128 v[160:163], v160 offset:3072
	ds_read_b128 v[164:167], v172
	ds_read_b128 v[168:171], v172 offset:1024
	ds_read_b128 v[180:183], v172 offset:2048
	ds_read_b128 v[198:201], v172 offset:3072
	v_lshl_add_u64 v[172:173], s[6:7], 0, v[134:135]
	s_add_i32 m0, s30, 0xc000
	ds_read_b128 v[202:205], v151
	ds_read_b128 v[206:209], v151 offset:1024
	ds_read_b128 v[210:213], v151 offset:2048
	ds_read_b128 v[214:217], v151 offset:3072
	ds_read_b128 v[218:221], v151 offset:4096
	ds_read_b128 v[222:225], v151 offset:5120
	ds_read_b128 v[226:229], v151 offset:6144
	ds_read_b128 v[230:233], v151 offset:7168
	global_load_lds_dwordx4 v[172:173], off
	v_lshl_add_u64 v[172:173], s[6:7], 0, v[136:137]
	s_add_i32 m0, s30, 0xe000
	s_nop 0
	global_load_lds_dwordx4 v[172:173], off
	s_waitcnt vmcnt(8)
	s_waitcnt lgkmcnt(0)
	s_setprio 1
	s_barrier
	v_mfma_f32_16x16x32_bf16 v[124:127], v[138:141], v[202:205], v[124:127]
	v_mfma_f32_16x16x32_bf16 v[120:123], v[156:159], v[202:205], v[120:123]
	v_mfma_f32_16x16x32_bf16 v[108:111], v[138:141], v[210:213], v[108:111]
	v_mfma_f32_16x16x32_bf16 v[104:107], v[156:159], v[210:213], v[104:107]
	v_mfma_f32_16x16x32_bf16 v[92:95], v[138:141], v[218:221], v[92:95]
	v_mfma_f32_16x16x32_bf16 v[88:91], v[156:159], v[218:221], v[88:91]
	v_mfma_f32_16x16x32_bf16 v[76:79], v[138:141], v[226:229], v[76:79]
	v_mfma_f32_16x16x32_bf16 v[72:75], v[156:159], v[226:229], v[72:75]
	v_mfma_f32_16x16x32_bf16 v[124:127], v[152:155], v[206:209], v[124:127]
	v_mfma_f32_16x16x32_bf16 v[120:123], v[160:163], v[206:209], v[120:123]
	v_mfma_f32_16x16x32_bf16 v[108:111], v[152:155], v[214:217], v[108:111]
	v_mfma_f32_16x16x32_bf16 v[104:107], v[160:163], v[214:217], v[104:107]
	v_mfma_f32_16x16x32_bf16 v[92:95], v[152:155], v[222:225], v[92:95]
	v_mfma_f32_16x16x32_bf16 v[88:91], v[160:163], v[222:225], v[88:91]
	v_mfma_f32_16x16x32_bf16 v[76:79], v[152:155], v[230:233], v[76:79]
	v_mfma_f32_16x16x32_bf16 v[72:75], v[160:163], v[230:233], v[72:75]
	s_setprio 0
	s_setprio 1
	v_mfma_f32_16x16x32_bf16 v[116:119], v[164:167], v[202:205], v[116:119]
	v_mfma_f32_16x16x32_bf16 v[112:115], v[180:183], v[202:205], v[112:115]
	v_mfma_f32_16x16x32_bf16 v[100:103], v[164:167], v[210:213], v[100:103]
	v_mfma_f32_16x16x32_bf16 v[96:99], v[180:183], v[210:213], v[96:99]
	v_mfma_f32_16x16x32_bf16 v[84:87], v[164:167], v[218:221], v[84:87]
	v_mfma_f32_16x16x32_bf16 v[80:83], v[180:183], v[218:221], v[80:83]
	v_mfma_f32_16x16x32_bf16 v[68:71], v[164:167], v[226:229], v[68:71]
	v_mfma_f32_16x16x32_bf16 v[64:67], v[180:183], v[226:229], v[64:67]
	v_mfma_f32_16x16x32_bf16 v[116:119], v[168:171], v[206:209], v[116:119]
	v_mfma_f32_16x16x32_bf16 v[112:115], v[198:201], v[206:209], v[112:115]
	v_mfma_f32_16x16x32_bf16 v[100:103], v[168:171], v[214:217], v[100:103]
	v_mfma_f32_16x16x32_bf16 v[96:99], v[198:201], v[214:217], v[96:99]
	v_mfma_f32_16x16x32_bf16 v[84:87], v[168:171], v[222:225], v[84:87]
	v_mfma_f32_16x16x32_bf16 v[80:83], v[198:201], v[222:225], v[80:83]
	v_mfma_f32_16x16x32_bf16 v[68:71], v[168:171], v[230:233], v[68:71]
	v_mfma_f32_16x16x32_bf16 v[64:67], v[198:201], v[230:233], v[64:67]
	s_barrier
	s_setprio 0
	s_add_i32 s6, s60, s29
	v_lshl_add_u64 v[172:173], s[4:5], 0, v[144:145]
	s_mov_b32 m0, s6
	ds_read_b128 v[202:205], v151 offset:16384
	ds_read_b128 v[206:209], v151 offset:17408
	ds_read_b128 v[210:213], v151 offset:18432
	ds_read_b128 v[214:217], v151 offset:19456
	ds_read_b128 v[218:221], v151 offset:20480
	ds_read_b128 v[222:225], v151 offset:21504
	ds_read_b128 v[226:229], v151 offset:22528
	ds_read_b128 v[230:233], v151 offset:23552
	global_load_lds_dwordx4 v[172:173], off
	s_add_i32 m0, s6, 0x2000
	s_add_u32 s6, s4, 0xb0000
	v_lshl_add_u64 v[184:185], s[4:5], 0, v[128:129]
	s_addc_u32 s7, s5, 0
	s_add_i32 s60, s61, s29
	global_load_lds_dwordx4 v[184:185], off
	v_lshl_add_u64 v[186:187], s[6:7], 0, v[144:145]
	s_mov_b32 m0, s60
	v_lshl_add_u64 v[188:189], s[24:25], 0, v[130:131]
	global_load_lds_dwordx4 v[186:187], off
	v_lshl_add_u64 v[186:187], s[6:7], 0, v[128:129]
	s_add_i32 m0, s60, 0x2000
	s_nop 0
	global_load_lds_dwordx4 v[186:187], off
	v_lshl_add_u64 v[186:187], s[24:25], 0, v[132:133]
	s_mov_b32 m0, s30
	s_nop 0
	global_load_lds_dwordx4 v[186:187], off
	s_mov_b32 m0, s31
	s_nop 0
	global_load_lds_dwordx4 v[188:189], off
	s_waitcnt vmcnt(8)
	s_waitcnt lgkmcnt(0)
	s_setprio 1
	s_barrier
; #define PG8_STAGE(bufoff, gbase, voff) do { _Pragma("unroll") for (int _i = 0; _i < 2; ++_i) \
;         __builtin_amdgcn_global_load_lds((const unsigned*)((const char*)(gbase) + (voff)[_i]), (PG8_LAS unsigned*)(lds + (bufoff) + ldsw + _i * 8192), 16, 0, 0); } while (0)
; #define PG8_LDA(dst, b, h) do { _Pragma("unroll") for (int m = 0; m < 4; ++m) _Pragma("unroll") for (int k = 0; k < 2; ++k) dst[m][k] = *(const PG8_LAS bf16x8*)(lds + PG8_SA(b, h) + aoff + m * 2048 + k * 1024); } while (0)
; #define PG8_LDB(dst, b, h) do { _Pragma("unroll") for (int n = 0; n < 2; ++n) _Pragma("unroll") for (int k = 0; k < 2; ++k) dst[n][k] = *(const PG8_LAS bf16x8*)(lds + PG8_SB(b, h) + boff + n * 2048 + k * 1024); } while (0)
; #define PG8_MMA(ai, bj, At, Bt) do { __builtin_amdgcn_s_setprio(1); _Pragma("unroll") for (int m = 0; m < 4; ++m) _Pragma("unroll") for (int n = 0; n < 2; ++n) _Pragma("unroll") for (int k = 0; k < 2; ++k) \
;         acc[ai][bj][m][n] = __builtin_amdgcn_mfma_f32_16x16x32_bf16(Bt[n][k], At[m][k], acc[ai][bj][m][n], 0, 0, 0); __builtin_amdgcn_s_setprio(0); } while (0)
; #define PG8_WAIT_V(n) asm volatile("s_waitcnt vmcnt(" #n ")" ::: "memory")
; #define PG8_WAIT_L(n) asm volatile("s_waitcnt lgkmcnt(" #n ")" ::: "memory")
; #define PG8_BAR __builtin_amdgcn_s_barrier()
; #define PG8_SCHED __builtin_amdgcn_sched_barrier(0)
; template <class Epi, class Sched, bool ALIGN_EPI = false, bool SP2 = false>
; __device__ __forceinline__ void gemm_phase(PG8_LAS unsigned char* lds, const Gemm g, const Sched& S, const Epi& E) {
;     ...
;             PG8_WAIT_V(8); PG8_WAIT_L(0); PG8_BAR; PG8_MMA(1, 0, At, B0); PG8_MMA(1, 1, At, B1); PG8_BAR; PG8_SCHED;
;             PG8_LDB(B0, 1, 0); PG8_LDB(B1, 1, 1); PG8_SCHED; PG8_LDA(At, 1, 0); PG8_STAGE(PG8_SA(0, 1), a2 + hstep, voffA);
;             PG8_WAIT_V(8); PG8_WAIT_L(0); PG8_BAR; PG8_MMA(0, 0, At, B0); PG8_MMA(0, 1, At, B1); PG8_BAR; PG8_SCHED;
	v_mfma_f32_16x16x32_bf16 v[60:63], v[138:141], v[202:205], v[60:63]
	v_mfma_f32_16x16x32_bf16 v[56:59], v[156:159], v[202:205], v[56:59]
	v_mfma_f32_16x16x32_bf16 v[44:47], v[138:141], v[210:213], v[44:47]
	v_mfma_f32_16x16x32_bf16 v[40:43], v[156:159], v[210:213], v[40:43]
	v_mfma_f32_16x16x32_bf16 v[28:31], v[138:141], v[218:221], v[28:31]
	v_mfma_f32_16x16x32_bf16 v[24:27], v[156:159], v[218:221], v[24:27]
	v_mfma_f32_16x16x32_bf16 v[12:15], v[138:141], v[226:229], v[12:15]
	v_mfma_f32_16x16x32_bf16 v[8:11], v[156:159], v[226:229], v[8:11]
	v_mfma_f32_16x16x32_bf16 v[60:63], v[152:155], v[206:209], v[60:63]
	v_mfma_f32_16x16x32_bf16 v[56:59], v[160:163], v[206:209], v[56:59]
	v_mfma_f32_16x16x32_bf16 v[44:47], v[152:155], v[214:217], v[44:47]
	v_mfma_f32_16x16x32_bf16 v[40:43], v[160:163], v[214:217], v[40:43]
	v_mfma_f32_16x16x32_bf16 v[28:31], v[152:155], v[222:225], v[28:31]
	v_mfma_f32_16x16x32_bf16 v[24:27], v[160:163], v[222:225], v[24:27]
	v_mfma_f32_16x16x32_bf16 v[12:15], v[152:155], v[230:233], v[12:15]
	v_mfma_f32_16x16x32_bf16 v[8:11], v[160:163], v[230:233], v[8:11]
	s_setprio 0
	s_setprio 1
	v_mfma_f32_16x16x32_bf16 v[52:55], v[164:167], v[202:205], v[52:55]
	v_mfma_f32_16x16x32_bf16 v[48:51], v[180:183], v[202:205], v[48:51]
	v_mfma_f32_16x16x32_bf16 v[36:39], v[164:167], v[210:213], v[36:39]
	v_mfma_f32_16x16x32_bf16 v[32:35], v[180:183], v[210:213], v[32:35]
	v_mfma_f32_16x16x32_bf16 v[20:23], v[164:167], v[218:221], v[20:23]
	v_mfma_f32_16x16x32_bf16 v[16:19], v[180:183], v[218:221], v[16:19]
	v_mfma_f32_16x16x32_bf16 v[4:7], v[164:167], v[226:229], v[4:7]
	v_mfma_f32_16x16x32_bf16 v[0:3], v[180:183], v[226:229], v[0:3]
	v_mfma_f32_16x16x32_bf16 v[52:55], v[168:171], v[206:209], v[52:55]
	v_mfma_f32_16x16x32_bf16 v[48:51], v[198:201], v[206:209], v[48:51]
	v_mfma_f32_16x16x32_bf16 v[36:39], v[168:171], v[214:217], v[36:39]
	v_mfma_f32_16x16x32_bf16 v[32:35], v[198:201], v[214:217], v[32:35]
	v_mfma_f32_16x16x32_bf16 v[20:23], v[168:171], v[222:225], v[20:23]
	v_mfma_f32_16x16x32_bf16 v[16:19], v[198:201], v[222:225], v[16:19]
	v_mfma_f32_16x16x32_bf16 v[4:7], v[168:171], v[230:233], v[4:7]
	v_mfma_f32_16x16x32_bf16 v[0:3], v[198:201], v[230:233], v[0:3]
	s_barrier
	s_setprio 0
	s_add_i32 s60, 0, 0x18000
	s_add_i32 s61, 0, 0x1c000
	v_add_u32_e32 v160, s60, v143
	v_add_u32_e32 v190, s61, v143
	ds_read_b128 v[138:141], v160
	ds_read_b128 v[152:155], v160 offset:1024
	ds_read_b128 v[156:159], v160 offset:2048
	ds_read_b128 v[160:163], v160 offset:3072
	ds_read_b128 v[164:167], v190
	ds_read_b128 v[168:171], v190 offset:1024
	ds_read_b128 v[180:183], v190 offset:2048
	ds_read_b128 v[198:201], v190 offset:3072
	s_add_u32 s6, s24, 0xb0000
	s_addc_u32 s7, s25, 0
	s_mov_b32 m0, s34
	v_lshl_add_u64 v[190:191], s[6:7], 0, v[132:133]
	ds_read_b128 v[202:205], v151 offset:32768
	ds_read_b128 v[206:209], v151 offset:33792
	ds_read_b128 v[210:213], v151 offset:34816
	ds_read_b128 v[214:217], v151 offset:35840
	ds_read_b128 v[218:221], v151 offset:36864
	ds_read_b128 v[222:225], v151 offset:37888
	ds_read_b128 v[226:229], v151 offset:38912
	ds_read_b128 v[230:233], v151 offset:39936
	global_load_lds_dwordx4 v[190:191], off
	v_lshl_add_u64 v[190:191], s[6:7], 0, v[130:131]
	s_mov_b32 m0, s35
	s_nop 0
	global_load_lds_dwordx4 v[190:191], off
	s_waitcnt vmcnt(8)
	s_waitcnt lgkmcnt(0)
	s_setprio 1
	s_barrier
	v_mfma_f32_16x16x32_bf16 v[124:127], v[138:141], v[202:205], v[124:127]
	v_mfma_f32_16x16x32_bf16 v[120:123], v[156:159], v[202:205], v[120:123]
	v_mfma_f32_16x16x32_bf16 v[108:111], v[138:141], v[210:213], v[108:111]
	v_mfma_f32_16x16x32_bf16 v[104:107], v[156:159], v[210:213], v[104:107]
	v_mfma_f32_16x16x32_bf16 v[92:95], v[138:141], v[218:221], v[92:95]
	v_mfma_f32_16x16x32_bf16 v[88:91], v[156:159], v[218:221], v[88:91]
	v_mfma_f32_16x16x32_bf16 v[76:79], v[138:141], v[226:229], v[76:79]
	v_mfma_f32_16x16x32_bf16 v[72:75], v[156:159], v[226:229], v[72:75]
	v_mfma_f32_16x16x32_bf16 v[124:127], v[152:155], v[206:209], v[124:127]
	v_mfma_f32_16x16x32_bf16 v[120:123], v[160:163], v[206:209], v[120:123]
	v_mfma_f32_16x16x32_bf16 v[108:111], v[152:155], v[214:217], v[108:111]
	v_mfma_f32_16x16x32_bf16 v[104:107], v[160:163], v[214:217], v[104:107]
	v_mfma_f32_16x16x32_bf16 v[92:95], v[152:155], v[222:225], v[92:95]
	v_mfma_f32_16x16x32_bf16 v[88:91], v[160:163], v[222:225], v[88:91]
	v_mfma_f32_16x16x32_bf16 v[76:79], v[152:155], v[230:233], v[76:79]
	v_mfma_f32_16x16x32_bf16 v[72:75], v[160:163], v[230:233], v[72:75]
	s_setprio 0
	s_setprio 1
	v_mfma_f32_16x16x32_bf16 v[116:119], v[164:167], v[202:205], v[116:119]
	v_mfma_f32_16x16x32_bf16 v[112:115], v[180:183], v[202:205], v[112:115]
	v_mfma_f32_16x16x32_bf16 v[100:103], v[164:167], v[210:213], v[100:103]
	v_mfma_f32_16x16x32_bf16 v[96:99], v[180:183], v[210:213], v[96:99]
	v_mfma_f32_16x16x32_bf16 v[84:87], v[164:167], v[218:221], v[84:87]
	v_mfma_f32_16x16x32_bf16 v[80:83], v[180:183], v[218:221], v[80:83]
	v_mfma_f32_16x16x32_bf16 v[68:71], v[164:167], v[226:229], v[68:71]
	v_mfma_f32_16x16x32_bf16 v[64:67], v[180:183], v[226:229], v[64:67]
	v_mfma_f32_16x16x32_bf16 v[116:119], v[168:171], v[206:209], v[116:119]
	v_mfma_f32_16x16x32_bf16 v[112:115], v[198:201], v[206:209], v[112:115]
	v_mfma_f32_16x16x32_bf16 v[100:103], v[168:171], v[214:217], v[100:103]
	v_mfma_f32_16x16x32_bf16 v[96:99], v[198:201], v[214:217], v[96:99]
	v_mfma_f32_16x16x32_bf16 v[84:87], v[168:171], v[222:225], v[84:87]
	v_mfma_f32_16x16x32_bf16 v[80:83], v[198:201], v[222:225], v[80:83]
	v_mfma_f32_16x16x32_bf16 v[68:71], v[168:171], v[230:233], v[68:71]
	v_mfma_f32_16x16x32_bf16 v[64:67], v[198:201], v[230:233], v[64:67]
	s_barrier
; #define PG8_STAGE(bufoff, gbase, voff) do { _Pragma("unroll") for (int _i = 0; _i < 2; ++_i) \
;         __builtin_amdgcn_global_load_lds((const unsigned*)((const char*)(gbase) + (voff)[_i]), (PG8_LAS unsigned*)(lds + (bufoff) + ldsw + _i * 8192), 16, 0, 0); } while (0)
; #define PG8_LDA(dst, b, h) do { _Pragma("unroll") for (int m = 0; m < 4; ++m) _Pragma("unroll") for (int k = 0; k < 2; ++k) dst[m][k] = *(const PG8_LAS bf16x8*)(lds + PG8_SA(b, h) + aoff + m * 2048 + k * 1024); } while (0)
; #define PG8_LDB(dst, b, h) do { _Pragma("unroll") for (int n = 0; n < 2; ++n) _Pragma("unroll") for (int k = 0; k < 2; ++k) dst[n][k] = *(const PG8_LAS bf16x8*)(lds + PG8_SB(b, h) + boff + n * 2048 + k * 1024); } while (0)
; #define PG8_MMA(ai, bj, At, Bt) do { __builtin_amdgcn_s_setprio(1); _Pragma("unroll") for (int m = 0; m < 4; ++m) _Pragma("unroll") for (int n = 0; n < 2; ++n) _Pragma("unroll") for (int k = 0; k < 2; ++k) \
;         acc[ai][bj][m][n] = __builtin_amdgcn_mfma_f32_16x16x32_bf16(Bt[n][k], At[m][k], acc[ai][bj][m][n], 0, 0, 0); __builtin_amdgcn_s_setprio(0); } while (0)
; #define PG8_WAIT_V(n) asm volatile("s_waitcnt vmcnt(" #n ")" ::: "memory")
; #define PG8_WAIT_L(n) asm volatile("s_waitcnt lgkmcnt(" #n ")" ::: "memory")
; #define PG8_BAR __builtin_amdgcn_s_barrier()
; #define PG8_SCHED __builtin_amdgcn_sched_barrier(0)
; template <class Epi, class Sched, bool ALIGN_EPI = false, bool SP2 = false>
; __device__ __forceinline__ void gemm_phase(PG8_LAS unsigned char* lds, const Gemm g, const Sched& S, const Epi& E) {
;     ...
;             PG8_LDB(B0, 1, 0); PG8_LDB(B1, 1, 1); PG8_SCHED; PG8_LDA(At, 1, 0); PG8_STAGE(PG8_SA(0, 1), a2 + hstep, voffA);
;             PG8_WAIT_V(8); PG8_WAIT_L(0); PG8_BAR; PG8_MMA(0, 0, At, B0); PG8_MMA(0, 1, At, B1); PG8_BAR; PG8_SCHED;
;             PG8_LDA(At, 1, 1); PG8_STAGE(PG8_SB(1, 0), b3, voffB); PG8_STAGE(PG8_SB(1, 1), b3 + hstep, voffB); PG8_STAGE(PG8_SA(1, 0), a3, voffA);
;             PG8_WAIT_V(8); PG8_WAIT_L(0); PG8_BAR; PG8_MMA(1, 0, At, B0); PG8_MMA(1, 1, At, B1); PG8_BAR; PG8_SCHED;
;     ...
;         if constexpr (ALIGN_EPI) { if (wr == 0) PG8_BAR; }
	s_setprio 0
	s_add_i32 s6, s60, s29
	v_lshl_add_u64 v[172:173], v[172:173], 0, s[94:95]
	s_mov_b32 m0, s6
	ds_read_b128 v[202:205], v151 offset:49152
	ds_read_b128 v[206:209], v151 offset:50176
	ds_read_b128 v[210:213], v151 offset:51200
	ds_read_b128 v[214:217], v151 offset:52224
	ds_read_b128 v[218:221], v151 offset:53248
	ds_read_b128 v[222:225], v151 offset:54272
	ds_read_b128 v[226:229], v151 offset:55296
	ds_read_b128 v[230:233], v151 offset:56320
	global_load_lds_dwordx4 v[172:173], off
	s_add_i32 m0, s6, 0x2000
	s_add_u32 s4, s4, 0xb0080
	v_lshl_add_u64 v[172:173], v[184:185], 0, s[94:95]
	s_addc_u32 s5, s5, 0
	s_add_i32 s6, s61, s29
	global_load_lds_dwordx4 v[172:173], off
	v_lshl_add_u64 v[172:173], s[4:5], 0, v[144:145]
	s_mov_b32 m0, s6
	s_nop 0
	global_load_lds_dwordx4 v[172:173], off
	v_lshl_add_u64 v[172:173], s[4:5], 0, v[128:129]
	s_add_i32 m0, s6, 0x2000
	s_nop 0
	global_load_lds_dwordx4 v[172:173], off
	v_lshl_add_u64 v[172:173], v[186:187], 0, s[94:95]
	s_mov_b32 m0, s50
	s_nop 0
	global_load_lds_dwordx4 v[172:173], off
	v_lshl_add_u64 v[172:173], v[188:189], 0, s[94:95]
	s_mov_b32 m0, s51
	s_nop 0
	global_load_lds_dwordx4 v[172:173], off
	s_waitcnt vmcnt(8)
	s_waitcnt lgkmcnt(0)
	s_setprio 1
	s_barrier
	v_mfma_f32_16x16x32_bf16 v[60:63], v[138:141], v[202:205], v[60:63]
	v_mfma_f32_16x16x32_bf16 v[56:59], v[156:159], v[202:205], v[56:59]
	v_mfma_f32_16x16x32_bf16 v[44:47], v[138:141], v[210:213], v[44:47]
	v_mfma_f32_16x16x32_bf16 v[40:43], v[156:159], v[210:213], v[40:43]
	v_mfma_f32_16x16x32_bf16 v[28:31], v[138:141], v[218:221], v[28:31]
	v_mfma_f32_16x16x32_bf16 v[24:27], v[156:159], v[218:221], v[24:27]
	v_mfma_f32_16x16x32_bf16 v[12:15], v[138:141], v[226:229], v[12:15]
	v_mfma_f32_16x16x32_bf16 v[8:11], v[156:159], v[226:229], v[8:11]
	v_mfma_f32_16x16x32_bf16 v[60:63], v[152:155], v[206:209], v[60:63]
	v_mfma_f32_16x16x32_bf16 v[56:59], v[160:163], v[206:209], v[56:59]
	v_mfma_f32_16x16x32_bf16 v[44:47], v[152:155], v[214:217], v[44:47]
	v_mfma_f32_16x16x32_bf16 v[40:43], v[160:163], v[214:217], v[40:43]
	v_mfma_f32_16x16x32_bf16 v[28:31], v[152:155], v[222:225], v[28:31]
	v_mfma_f32_16x16x32_bf16 v[24:27], v[160:163], v[222:225], v[24:27]
	v_mfma_f32_16x16x32_bf16 v[12:15], v[152:155], v[230:233], v[12:15]
	v_mfma_f32_16x16x32_bf16 v[8:11], v[160:163], v[230:233], v[8:11]
	s_setprio 0
	s_setprio 1
	v_mfma_f32_16x16x32_bf16 v[52:55], v[164:167], v[202:205], v[52:55]
	v_mfma_f32_16x16x32_bf16 v[48:51], v[180:183], v[202:205], v[48:51]
	v_mfma_f32_16x16x32_bf16 v[36:39], v[164:167], v[210:213], v[36:39]
	v_mfma_f32_16x16x32_bf16 v[32:35], v[180:183], v[210:213], v[32:35]
	v_mfma_f32_16x16x32_bf16 v[20:23], v[164:167], v[218:221], v[20:23]
	v_mfma_f32_16x16x32_bf16 v[16:19], v[180:183], v[218:221], v[16:19]
	v_mfma_f32_16x16x32_bf16 v[4:7], v[164:167], v[226:229], v[4:7]
	v_mfma_f32_16x16x32_bf16 v[0:3], v[180:183], v[226:229], v[0:3]
	v_mfma_f32_16x16x32_bf16 v[52:55], v[168:171], v[206:209], v[52:55]
	v_mfma_f32_16x16x32_bf16 v[48:51], v[198:201], v[206:209], v[48:51]
	v_mfma_f32_16x16x32_bf16 v[36:39], v[168:171], v[214:217], v[36:39]
	v_mfma_f32_16x16x32_bf16 v[32:35], v[198:201], v[214:217], v[32:35]
	v_mfma_f32_16x16x32_bf16 v[20:23], v[168:171], v[222:225], v[20:23]
	v_mfma_f32_16x16x32_bf16 v[16:19], v[198:201], v[222:225], v[16:19]
	v_mfma_f32_16x16x32_bf16 v[4:7], v[168:171], v[230:233], v[4:7]
	v_mfma_f32_16x16x32_bf16 v[0:3], v[198:201], v[230:233], v[0:3]
	s_barrier
	s_setprio 0
	s_add_i32 s59, s59, 2
	s_add_u32 s57, s57, 0x100
	s_addc_u32 s58, s58, 0
	s_cmp_gt_u32 s59, 41
	s_mov_b64 s[6:7], s[0:1]
	s_cbranch_scc0 .LBB0_1900
	s_and_b64 vcc, exec, s[46:47]
	s_cbranch_vccz .LBB0_1903
	s_barrier
